# GDN: three staged lgkmcnt waits (5,3,0) instead of five
# baseline (speedup 1.0000x reference)
.Lgd2_loop:
	global_load_dword v108, v36, s[8:9]
	global_load_dword v109, v36, s[8:9] offset:-2048
	global_load_dword v111, v104, s[8:9] offset:2048
	global_load_dword v110, v37, s[10:11]
	global_load_dword v112, v105, s[10:11]
	global_load_dword v113, v106, s[12:13]
	s_add_u32 s8, s8, 0xc000
	s_addc_u32 s9, s9, 0
	s_add_u32 s10, s10, 0x20000
	s_addc_u32 s11, s11, 0
	s_add_u32 s12, s12, 0x400
	s_addc_u32 s13, s13, 0
	s_waitcnt lgkmcnt(5)
	v_pk_mul_f32 v[38:39], v[6:7], v[56:57] op_sel_hi:[1,0]
	v_pk_mul_f32 v[40:41], v[6:7], v[56:57] op_sel:[0,1] op_sel_hi:[1,1]
	v_pk_fma_f32 v[38:39], v[8:9], v[58:59], v[38:39] op_sel_hi:[1,0,1]
	v_pk_fma_f32 v[40:41], v[8:9], v[58:59], v[40:41] op_sel:[0,1,0] op_sel_hi:[1,1,1]
	s_waitcnt lgkmcnt(3)
	v_pk_fma_f32 v[38:39], v[10:11], v[60:61], v[38:39] op_sel_hi:[1,0,1]
	v_pk_fma_f32 v[40:41], v[10:11], v[60:61], v[40:41] op_sel:[0,1,0] op_sel_hi:[1,1,1]
	v_pk_fma_f32 v[38:39], v[12:13], v[62:63], v[38:39] op_sel_hi:[1,0,1]
	v_pk_fma_f32 v[40:41], v[12:13], v[62:63], v[40:41] op_sel:[0,1,0] op_sel_hi:[1,1,1]
	v_pk_fma_f32 v[38:39], v[14:15], v[64:65], v[38:39] op_sel_hi:[1,0,1]
	v_pk_fma_f32 v[40:41], v[14:15], v[64:65], v[40:41] op_sel:[0,1,0] op_sel_hi:[1,1,1]
	v_pk_fma_f32 v[38:39], v[16:17], v[66:67], v[38:39] op_sel_hi:[1,0,1]
	v_pk_fma_f32 v[40:41], v[16:17], v[66:67], v[40:41] op_sel:[0,1,0] op_sel_hi:[1,1,1]
	s_waitcnt lgkmcnt(0)
	v_pk_fma_f32 v[38:39], v[18:19], v[68:69], v[38:39] op_sel_hi:[1,0,1]
	v_pk_fma_f32 v[40:41], v[18:19], v[68:69], v[40:41] op_sel:[0,1,0] op_sel_hi:[1,1,1]
	v_pk_fma_f32 v[38:39], v[20:21], v[70:71], v[38:39] op_sel_hi:[1,0,1]
	v_pk_fma_f32 v[40:41], v[20:21], v[70:71], v[40:41] op_sel:[0,1,0] op_sel_hi:[1,1,1]
	v_mul_f32_e32 v50, v76, v51
	v_add_f32_dpp v38, v38, v38 row_ror:8 row_mask:0xf bank_mask:0x3 bound_ctrl:1
	v_add_f32_dpp v39, v39, v39 row_ror:8 row_mask:0xf bank_mask:0x3 bound_ctrl:1
	v_add_f32_dpp v38, v40, v40 row_ror:8 row_mask:0xf bank_mask:0xc bound_ctrl:1
	v_add_f32_dpp v39, v41, v41 row_ror:8 row_mask:0xf bank_mask:0xc bound_ctrl:1
	ds_read_b128 v[80:83], v2 offset:1280
	v_add_f32_dpp v38, v38, v38 row_half_mirror row_mask:0xf bank_mask:0x5 bound_ctrl:1
	v_add_f32_dpp v38, v39, v39 row_half_mirror row_mask:0xf bank_mask:0xa bound_ctrl:1
	ds_read_b128 v[84:87], v2 offset:1536
	ds_read_b128 v[88:91], v2 offset:1792
	v_add_f32_dpp v38, v38, v38 quad_perm:[1,0,3,2] row_mask:0xf bank_mask:0xf bound_ctrl:1
	ds_read_b128 v[92:95], v2 offset:2048
	ds_read_b64 v[96:97], v3 offset:12800
	v_add_f32_dpp v38, v38, v38 quad_perm:[2,3,0,1] row_mask:0xf bank_mask:0xf bound_ctrl:1
	ds_read_b128 v[100:103], v1 offset:14608
	v_cmp_gt_f32_e32 vcc, 0x2b8cbccc, v50
	v_fmac_f32_dpp v72, -v38, v50 row_newbcast:0 row_mask:0xf bank_mask:0xf bound_ctrl:1
	v_fmac_f32_dpp v73, -v38, v50 row_newbcast:4 row_mask:0xf bank_mask:0xf bound_ctrl:1
	v_pk_mul_f32 v[44:45], v[72:73], v[76:77] op_sel:[0,1] op_sel_hi:[1,1]
	v_pk_mul_f32 v[48:49], v[44:45], v[78:79] op_sel_hi:[1,0]
	v_rcp_f32_e32 v52, v50
	s_add_u32 s14, s14, 0x1000
	s_addc_u32 s15, s15, 0
	v_fmac_f32_dpp v48, v38, v50 row_newbcast:8 row_mask:0xf bank_mask:0xf bound_ctrl:1
	v_fmac_f32_dpp v49, v38, v50 row_newbcast:12 row_mask:0xf bank_mask:0xf bound_ctrl:1
	s_cbranch_vccnz .Lgd2_rare0_0
.Lgd2_back0_0:
	v_cvt_pk_bf16_f32 v54, v48, v49
	v_pk_mul_f32 v[46:47], v[44:45], v[52:53] op_sel_hi:[1,0]
	v_pk_fma_f32 v[6:7], v[56:57], v[46:47], v[6:7] op_sel_hi:[0,1,1]
	v_pk_fma_f32 v[8:9], v[58:59], v[46:47], v[8:9] op_sel_hi:[0,1,1]
	v_pk_fma_f32 v[10:11], v[60:61], v[46:47], v[10:11] op_sel_hi:[0,1,1]
	v_pk_fma_f32 v[12:13], v[62:63], v[46:47], v[12:13] op_sel_hi:[0,1,1]
	v_pk_fma_f32 v[14:15], v[64:65], v[46:47], v[14:15] op_sel_hi:[0,1,1]
	v_pk_fma_f32 v[16:17], v[66:67], v[46:47], v[16:17] op_sel_hi:[0,1,1]
	v_pk_fma_f32 v[18:19], v[68:69], v[46:47], v[18:19] op_sel_hi:[0,1,1]
	v_pk_fma_f32 v[20:21], v[70:71], v[46:47], v[20:21] op_sel_hi:[0,1,1]
	global_store_dword v154, v54, s[14:15] offset:-4096
	s_waitcnt lgkmcnt(5)
	v_pk_mul_f32 v[38:39], v[6:7], v[80:81] op_sel_hi:[1,0]
	v_pk_mul_f32 v[40:41], v[6:7], v[80:81] op_sel:[0,1] op_sel_hi:[1,1]
	v_pk_fma_f32 v[38:39], v[8:9], v[82:83], v[38:39] op_sel_hi:[1,0,1]
	v_pk_fma_f32 v[40:41], v[8:9], v[82:83], v[40:41] op_sel:[0,1,0] op_sel_hi:[1,1,1]
	s_waitcnt lgkmcnt(3)
	v_pk_fma_f32 v[38:39], v[10:11], v[84:85], v[38:39] op_sel_hi:[1,0,1]
	v_pk_fma_f32 v[40:41], v[10:11], v[84:85], v[40:41] op_sel:[0,1,0] op_sel_hi:[1,1,1]
	v_pk_fma_f32 v[38:39], v[12:13], v[86:87], v[38:39] op_sel_hi:[1,0,1]
	v_pk_fma_f32 v[40:41], v[12:13], v[86:87], v[40:41] op_sel:[0,1,0] op_sel_hi:[1,1,1]
	v_pk_fma_f32 v[38:39], v[14:15], v[88:89], v[38:39] op_sel_hi:[1,0,1]
	v_pk_fma_f32 v[40:41], v[14:15], v[88:89], v[40:41] op_sel:[0,1,0] op_sel_hi:[1,1,1]
	v_pk_fma_f32 v[38:39], v[16:17], v[90:91], v[38:39] op_sel_hi:[1,0,1]
	v_pk_fma_f32 v[40:41], v[16:17], v[90:91], v[40:41] op_sel:[0,1,0] op_sel_hi:[1,1,1]
	s_waitcnt lgkmcnt(0)
	v_pk_fma_f32 v[38:39], v[18:19], v[92:93], v[38:39] op_sel_hi:[1,0,1]
	v_pk_fma_f32 v[40:41], v[18:19], v[92:93], v[40:41] op_sel:[0,1,0] op_sel_hi:[1,1,1]
	v_pk_fma_f32 v[38:39], v[20:21], v[94:95], v[38:39] op_sel_hi:[1,0,1]
	v_pk_fma_f32 v[40:41], v[20:21], v[94:95], v[40:41] op_sel:[0,1,0] op_sel_hi:[1,1,1]
	v_mul_f32_e32 v51, v100, v50
	v_add_f32_dpp v38, v38, v38 row_ror:8 row_mask:0xf bank_mask:0x3 bound_ctrl:1
	v_add_f32_dpp v39, v39, v39 row_ror:8 row_mask:0xf bank_mask:0x3 bound_ctrl:1
	v_add_f32_dpp v38, v40, v40 row_ror:8 row_mask:0xf bank_mask:0xc bound_ctrl:1
	v_add_f32_dpp v39, v41, v41 row_ror:8 row_mask:0xf bank_mask:0xc bound_ctrl:1
	ds_read_b128 v[56:59], v2 offset:2304
	v_add_f32_dpp v38, v38, v38 row_half_mirror row_mask:0xf bank_mask:0x5 bound_ctrl:1
	v_add_f32_dpp v38, v39, v39 row_half_mirror row_mask:0xf bank_mask:0xa bound_ctrl:1
	ds_read_b128 v[60:63], v2 offset:2560
	ds_read_b128 v[64:67], v2 offset:2816
	v_add_f32_dpp v38, v38, v38 quad_perm:[1,0,3,2] row_mask:0xf bank_mask:0xf bound_ctrl:1
	ds_read_b128 v[68:71], v2 offset:3072
	ds_read_b64 v[72:73], v3 offset:13056
	v_add_f32_dpp v38, v38, v38 quad_perm:[2,3,0,1] row_mask:0xf bank_mask:0xf bound_ctrl:1
	ds_read_b128 v[76:79], v1 offset:14624
	v_cmp_gt_f32_e32 vcc, 0x2b8cbccc, v51
	v_fmac_f32_dpp v96, -v38, v51 row_newbcast:0 row_mask:0xf bank_mask:0xf bound_ctrl:1
	v_fmac_f32_dpp v97, -v38, v51 row_newbcast:4 row_mask:0xf bank_mask:0xf bound_ctrl:1
	v_pk_mul_f32 v[44:45], v[96:97], v[100:101] op_sel:[0,1] op_sel_hi:[1,1]
	v_pk_mul_f32 v[48:49], v[44:45], v[102:103] op_sel_hi:[1,0]
	v_rcp_f32_e32 v52, v51
	s_add_u32 s14, s14, 0x1000
	s_addc_u32 s15, s15, 0
	v_fmac_f32_dpp v48, v38, v51 row_newbcast:8 row_mask:0xf bank_mask:0xf bound_ctrl:1
	v_fmac_f32_dpp v49, v38, v51 row_newbcast:12 row_mask:0xf bank_mask:0xf bound_ctrl:1
	s_cbranch_vccnz .Lgd2_rare0_1
.Lgd2_back0_1:
	v_cvt_pk_bf16_f32 v54, v48, v49
	v_pk_mul_f32 v[46:47], v[44:45], v[52:53] op_sel_hi:[1,0]
	v_pk_fma_f32 v[6:7], v[80:81], v[46:47], v[6:7] op_sel_hi:[0,1,1]
	v_pk_fma_f32 v[8:9], v[82:83], v[46:47], v[8:9] op_sel_hi:[0,1,1]
	v_pk_fma_f32 v[10:11], v[84:85], v[46:47], v[10:11] op_sel_hi:[0,1,1]
	v_pk_fma_f32 v[12:13], v[86:87], v[46:47], v[12:13] op_sel_hi:[0,1,1]
	v_pk_fma_f32 v[14:15], v[88:89], v[46:47], v[14:15] op_sel_hi:[0,1,1]
	v_pk_fma_f32 v[16:17], v[90:91], v[46:47], v[16:17] op_sel_hi:[0,1,1]
	v_pk_fma_f32 v[18:19], v[92:93], v[46:47], v[18:19] op_sel_hi:[0,1,1]
	v_pk_fma_f32 v[20:21], v[94:95], v[46:47], v[20:21] op_sel_hi:[0,1,1]
	global_store_dword v154, v54, s[14:15] offset:-4096
	s_waitcnt lgkmcnt(5)
	v_pk_mul_f32 v[38:39], v[6:7], v[56:57] op_sel_hi:[1,0]
	v_pk_mul_f32 v[40:41], v[6:7], v[56:57] op_sel:[0,1] op_sel_hi:[1,1]
	v_pk_fma_f32 v[38:39], v[8:9], v[58:59], v[38:39] op_sel_hi:[1,0,1]
	v_pk_fma_f32 v[40:41], v[8:9], v[58:59], v[40:41] op_sel:[0,1,0] op_sel_hi:[1,1,1]
	s_waitcnt lgkmcnt(3)
	v_pk_fma_f32 v[38:39], v[10:11], v[60:61], v[38:39] op_sel_hi:[1,0,1]
	v_pk_fma_f32 v[40:41], v[10:11], v[60:61], v[40:41] op_sel:[0,1,0] op_sel_hi:[1,1,1]
	v_pk_fma_f32 v[38:39], v[12:13], v[62:63], v[38:39] op_sel_hi:[1,0,1]
	v_pk_fma_f32 v[40:41], v[12:13], v[62:63], v[40:41] op_sel:[0,1,0] op_sel_hi:[1,1,1]
	v_pk_fma_f32 v[38:39], v[14:15], v[64:65], v[38:39] op_sel_hi:[1,0,1]
	v_pk_fma_f32 v[40:41], v[14:15], v[64:65], v[40:41] op_sel:[0,1,0] op_sel_hi:[1,1,1]
	v_pk_fma_f32 v[38:39], v[16:17], v[66:67], v[38:39] op_sel_hi:[1,0,1]
	v_pk_fma_f32 v[40:41], v[16:17], v[66:67], v[40:41] op_sel:[0,1,0] op_sel_hi:[1,1,1]
	s_waitcnt lgkmcnt(0)
	v_pk_fma_f32 v[38:39], v[18:19], v[68:69], v[38:39] op_sel_hi:[1,0,1]
	v_pk_fma_f32 v[40:41], v[18:19], v[68:69], v[40:41] op_sel:[0,1,0] op_sel_hi:[1,1,1]
	v_pk_fma_f32 v[38:39], v[20:21], v[70:71], v[38:39] op_sel_hi:[1,0,1]
	v_pk_fma_f32 v[40:41], v[20:21], v[70:71], v[40:41] op_sel:[0,1,0] op_sel_hi:[1,1,1]
	v_mul_f32_e32 v50, v76, v51
	v_add_f32_dpp v38, v38, v38 row_ror:8 row_mask:0xf bank_mask:0x3 bound_ctrl:1
	v_add_f32_dpp v39, v39, v39 row_ror:8 row_mask:0xf bank_mask:0x3 bound_ctrl:1
	v_add_f32_dpp v38, v40, v40 row_ror:8 row_mask:0xf bank_mask:0xc bound_ctrl:1
	v_add_f32_dpp v39, v41, v41 row_ror:8 row_mask:0xf bank_mask:0xc bound_ctrl:1
	ds_read_b128 v[80:83], v2 offset:3328
	v_add_f32_dpp v38, v38, v38 row_half_mirror row_mask:0xf bank_mask:0x5 bound_ctrl:1
	v_add_f32_dpp v38, v39, v39 row_half_mirror row_mask:0xf bank_mask:0xa bound_ctrl:1
	ds_read_b128 v[84:87], v2 offset:3584
	ds_read_b128 v[88:91], v2 offset:3840
	v_add_f32_dpp v38, v38, v38 quad_perm:[1,0,3,2] row_mask:0xf bank_mask:0xf bound_ctrl:1
	ds_read_b128 v[92:95], v2 offset:4096
	ds_read_b64 v[96:97], v3 offset:13312
	v_add_f32_dpp v38, v38, v38 quad_perm:[2,3,0,1] row_mask:0xf bank_mask:0xf bound_ctrl:1
	ds_read_b128 v[100:103], v1 offset:14640
	v_cmp_gt_f32_e32 vcc, 0x2b8cbccc, v50
	v_fmac_f32_dpp v72, -v38, v50 row_newbcast:0 row_mask:0xf bank_mask:0xf bound_ctrl:1
	v_fmac_f32_dpp v73, -v38, v50 row_newbcast:4 row_mask:0xf bank_mask:0xf bound_ctrl:1
	v_pk_mul_f32 v[44:45], v[72:73], v[76:77] op_sel:[0,1] op_sel_hi:[1,1]
	v_pk_mul_f32 v[48:49], v[44:45], v[78:79] op_sel_hi:[1,0]
	v_rcp_f32_e32 v52, v50
	s_add_u32 s14, s14, 0x1000
	s_addc_u32 s15, s15, 0
	v_fmac_f32_dpp v48, v38, v50 row_newbcast:8 row_mask:0xf bank_mask:0xf bound_ctrl:1
	v_fmac_f32_dpp v49, v38, v50 row_newbcast:12 row_mask:0xf bank_mask:0xf bound_ctrl:1
	s_cbranch_vccnz .Lgd2_rare0_2
.Lgd2_back0_2:
	v_cvt_pk_bf16_f32 v54, v48, v49
	v_pk_mul_f32 v[46:47], v[44:45], v[52:53] op_sel_hi:[1,0]
	v_pk_fma_f32 v[6:7], v[56:57], v[46:47], v[6:7] op_sel_hi:[0,1,1]
	v_pk_fma_f32 v[8:9], v[58:59], v[46:47], v[8:9] op_sel_hi:[0,1,1]
	v_pk_fma_f32 v[10:11], v[60:61], v[46:47], v[10:11] op_sel_hi:[0,1,1]
	v_pk_fma_f32 v[12:13], v[62:63], v[46:47], v[12:13] op_sel_hi:[0,1,1]
	v_pk_fma_f32 v[14:15], v[64:65], v[46:47], v[14:15] op_sel_hi:[0,1,1]
	v_pk_fma_f32 v[16:17], v[66:67], v[46:47], v[16:17] op_sel_hi:[0,1,1]
	v_pk_fma_f32 v[18:19], v[68:69], v[46:47], v[18:19] op_sel_hi:[0,1,1]
	v_pk_fma_f32 v[20:21], v[70:71], v[46:47], v[20:21] op_sel_hi:[0,1,1]
	global_store_dword v154, v54, s[14:15] offset:-4096
	s_waitcnt lgkmcnt(5)
	v_pk_mul_f32 v[38:39], v[6:7], v[80:81] op_sel_hi:[1,0]
	v_pk_mul_f32 v[40:41], v[6:7], v[80:81] op_sel:[0,1] op_sel_hi:[1,1]
	v_pk_fma_f32 v[38:39], v[8:9], v[82:83], v[38:39] op_sel_hi:[1,0,1]
	v_pk_fma_f32 v[40:41], v[8:9], v[82:83], v[40:41] op_sel:[0,1,0] op_sel_hi:[1,1,1]
	s_waitcnt lgkmcnt(3)
	v_pk_fma_f32 v[38:39], v[10:11], v[84:85], v[38:39] op_sel_hi:[1,0,1]
	v_pk_fma_f32 v[40:41], v[10:11], v[84:85], v[40:41] op_sel:[0,1,0] op_sel_hi:[1,1,1]
	v_pk_fma_f32 v[38:39], v[12:13], v[86:87], v[38:39] op_sel_hi:[1,0,1]
	v_pk_fma_f32 v[40:41], v[12:13], v[86:87], v[40:41] op_sel:[0,1,0] op_sel_hi:[1,1,1]
	v_pk_fma_f32 v[38:39], v[14:15], v[88:89], v[38:39] op_sel_hi:[1,0,1]
	v_pk_fma_f32 v[40:41], v[14:15], v[88:89], v[40:41] op_sel:[0,1,0] op_sel_hi:[1,1,1]
	v_pk_fma_f32 v[38:39], v[16:17], v[90:91], v[38:39] op_sel_hi:[1,0,1]
	v_pk_fma_f32 v[40:41], v[16:17], v[90:91], v[40:41] op_sel:[0,1,0] op_sel_hi:[1,1,1]
	s_waitcnt lgkmcnt(0)
	v_pk_fma_f32 v[38:39], v[18:19], v[92:93], v[38:39] op_sel_hi:[1,0,1]
	v_pk_fma_f32 v[40:41], v[18:19], v[92:93], v[40:41] op_sel:[0,1,0] op_sel_hi:[1,1,1]
	v_pk_fma_f32 v[38:39], v[20:21], v[94:95], v[38:39] op_sel_hi:[1,0,1]
	v_pk_fma_f32 v[40:41], v[20:21], v[94:95], v[40:41] op_sel:[0,1,0] op_sel_hi:[1,1,1]
	v_mul_f32_e32 v51, v100, v50
	v_add_f32_dpp v38, v38, v38 row_ror:8 row_mask:0xf bank_mask:0x3 bound_ctrl:1
	v_add_f32_dpp v39, v39, v39 row_ror:8 row_mask:0xf bank_mask:0x3 bound_ctrl:1
	v_add_f32_dpp v38, v40, v40 row_ror:8 row_mask:0xf bank_mask:0xc bound_ctrl:1
	v_add_f32_dpp v39, v41, v41 row_ror:8 row_mask:0xf bank_mask:0xc bound_ctrl:1
	ds_read_b128 v[56:59], v2 offset:4352
	v_add_f32_dpp v38, v38, v38 row_half_mirror row_mask:0xf bank_mask:0x5 bound_ctrl:1
	v_add_f32_dpp v38, v39, v39 row_half_mirror row_mask:0xf bank_mask:0xa bound_ctrl:1
	ds_read_b128 v[60:63], v2 offset:4608
	ds_read_b128 v[64:67], v2 offset:4864
	v_add_f32_dpp v38, v38, v38 quad_perm:[1,0,3,2] row_mask:0xf bank_mask:0xf bound_ctrl:1
	ds_read_b128 v[68:71], v2 offset:5120
	ds_read_b64 v[72:73], v3 offset:13568
	v_add_f32_dpp v38, v38, v38 quad_perm:[2,3,0,1] row_mask:0xf bank_mask:0xf bound_ctrl:1
	ds_read_b128 v[76:79], v1 offset:14656
	v_cmp_gt_f32_e32 vcc, 0x2b8cbccc, v51
	v_fmac_f32_dpp v96, -v38, v51 row_newbcast:0 row_mask:0xf bank_mask:0xf bound_ctrl:1
	v_fmac_f32_dpp v97, -v38, v51 row_newbcast:4 row_mask:0xf bank_mask:0xf bound_ctrl:1
	v_pk_mul_f32 v[44:45], v[96:97], v[100:101] op_sel:[0,1] op_sel_hi:[1,1]
	v_pk_mul_f32 v[48:49], v[44:45], v[102:103] op_sel_hi:[1,0]
	v_rcp_f32_e32 v52, v51
	s_add_u32 s14, s14, 0x1000
	s_addc_u32 s15, s15, 0
	v_fmac_f32_dpp v48, v38, v51 row_newbcast:8 row_mask:0xf bank_mask:0xf bound_ctrl:1
	v_fmac_f32_dpp v49, v38, v51 row_newbcast:12 row_mask:0xf bank_mask:0xf bound_ctrl:1
	s_cbranch_vccnz .Lgd2_rare0_3
.Lgd2_back0_3:
	v_cvt_pk_bf16_f32 v54, v48, v49
	v_pk_mul_f32 v[46:47], v[44:45], v[52:53] op_sel_hi:[1,0]
	v_pk_fma_f32 v[6:7], v[80:81], v[46:47], v[6:7] op_sel_hi:[0,1,1]
	v_pk_fma_f32 v[8:9], v[82:83], v[46:47], v[8:9] op_sel_hi:[0,1,1]
	v_pk_fma_f32 v[10:11], v[84:85], v[46:47], v[10:11] op_sel_hi:[0,1,1]
	v_pk_fma_f32 v[12:13], v[86:87], v[46:47], v[12:13] op_sel_hi:[0,1,1]
	v_pk_fma_f32 v[14:15], v[88:89], v[46:47], v[14:15] op_sel_hi:[0,1,1]
	v_pk_fma_f32 v[16:17], v[90:91], v[46:47], v[16:17] op_sel_hi:[0,1,1]
	v_pk_fma_f32 v[18:19], v[92:93], v[46:47], v[18:19] op_sel_hi:[0,1,1]
	v_pk_fma_f32 v[20:21], v[94:95], v[46:47], v[20:21] op_sel_hi:[0,1,1]
	global_store_dword v154, v54, s[14:15] offset:-4096
	s_waitcnt lgkmcnt(5)
	v_pk_mul_f32 v[38:39], v[6:7], v[56:57] op_sel_hi:[1,0]
	v_pk_mul_f32 v[40:41], v[6:7], v[56:57] op_sel:[0,1] op_sel_hi:[1,1]
	v_pk_fma_f32 v[38:39], v[8:9], v[58:59], v[38:39] op_sel_hi:[1,0,1]
	v_pk_fma_f32 v[40:41], v[8:9], v[58:59], v[40:41] op_sel:[0,1,0] op_sel_hi:[1,1,1]
	s_waitcnt lgkmcnt(3)
	v_pk_fma_f32 v[38:39], v[10:11], v[60:61], v[38:39] op_sel_hi:[1,0,1]
	v_pk_fma_f32 v[40:41], v[10:11], v[60:61], v[40:41] op_sel:[0,1,0] op_sel_hi:[1,1,1]
	v_pk_fma_f32 v[38:39], v[12:13], v[62:63], v[38:39] op_sel_hi:[1,0,1]
	v_pk_fma_f32 v[40:41], v[12:13], v[62:63], v[40:41] op_sel:[0,1,0] op_sel_hi:[1,1,1]
	v_pk_fma_f32 v[38:39], v[14:15], v[64:65], v[38:39] op_sel_hi:[1,0,1]
	v_pk_fma_f32 v[40:41], v[14:15], v[64:65], v[40:41] op_sel:[0,1,0] op_sel_hi:[1,1,1]
	v_pk_fma_f32 v[38:39], v[16:17], v[66:67], v[38:39] op_sel_hi:[1,0,1]
	v_pk_fma_f32 v[40:41], v[16:17], v[66:67], v[40:41] op_sel:[0,1,0] op_sel_hi:[1,1,1]
	s_waitcnt lgkmcnt(0)
	v_pk_fma_f32 v[38:39], v[18:19], v[68:69], v[38:39] op_sel_hi:[1,0,1]
	v_pk_fma_f32 v[40:41], v[18:19], v[68:69], v[40:41] op_sel:[0,1,0] op_sel_hi:[1,1,1]
	v_pk_fma_f32 v[38:39], v[20:21], v[70:71], v[38:39] op_sel_hi:[1,0,1]
	v_pk_fma_f32 v[40:41], v[20:21], v[70:71], v[40:41] op_sel:[0,1,0] op_sel_hi:[1,1,1]
	v_mul_f32_e32 v50, v76, v51
	v_add_f32_dpp v38, v38, v38 row_ror:8 row_mask:0xf bank_mask:0x3 bound_ctrl:1
	v_add_f32_dpp v39, v39, v39 row_ror:8 row_mask:0xf bank_mask:0x3 bound_ctrl:1
	v_add_f32_dpp v38, v40, v40 row_ror:8 row_mask:0xf bank_mask:0xc bound_ctrl:1
	v_add_f32_dpp v39, v41, v41 row_ror:8 row_mask:0xf bank_mask:0xc bound_ctrl:1
	ds_read_b128 v[80:83], v2 offset:5376
	v_add_f32_dpp v38, v38, v38 row_half_mirror row_mask:0xf bank_mask:0x5 bound_ctrl:1
	v_add_f32_dpp v38, v39, v39 row_half_mirror row_mask:0xf bank_mask:0xa bound_ctrl:1
	ds_read_b128 v[84:87], v2 offset:5632
	ds_read_b128 v[88:91], v2 offset:5888
	v_add_f32_dpp v38, v38, v38 quad_perm:[1,0,3,2] row_mask:0xf bank_mask:0xf bound_ctrl:1
	ds_read_b128 v[92:95], v2 offset:6144
	ds_read_b64 v[96:97], v3 offset:13824
	v_add_f32_dpp v38, v38, v38 quad_perm:[2,3,0,1] row_mask:0xf bank_mask:0xf bound_ctrl:1
	ds_read_b128 v[100:103], v1 offset:14672
	v_cmp_gt_f32_e32 vcc, 0x2b8cbccc, v50
	v_fmac_f32_dpp v72, -v38, v50 row_newbcast:0 row_mask:0xf bank_mask:0xf bound_ctrl:1
	v_fmac_f32_dpp v73, -v38, v50 row_newbcast:4 row_mask:0xf bank_mask:0xf bound_ctrl:1
	v_pk_mul_f32 v[44:45], v[72:73], v[76:77] op_sel:[0,1] op_sel_hi:[1,1]
	v_pk_mul_f32 v[48:49], v[44:45], v[78:79] op_sel_hi:[1,0]
	v_rcp_f32_e32 v52, v50
	s_add_u32 s14, s14, 0x1000
	s_addc_u32 s15, s15, 0
	v_fmac_f32_dpp v48, v38, v50 row_newbcast:8 row_mask:0xf bank_mask:0xf bound_ctrl:1
	v_fmac_f32_dpp v49, v38, v50 row_newbcast:12 row_mask:0xf bank_mask:0xf bound_ctrl:1
	s_cbranch_vccnz .Lgd2_rare0_4
.Lgd2_back0_4:
	v_cvt_pk_bf16_f32 v54, v48, v49
	v_pk_mul_f32 v[46:47], v[44:45], v[52:53] op_sel_hi:[1,0]
	v_pk_fma_f32 v[6:7], v[56:57], v[46:47], v[6:7] op_sel_hi:[0,1,1]
	v_pk_fma_f32 v[8:9], v[58:59], v[46:47], v[8:9] op_sel_hi:[0,1,1]
	v_pk_fma_f32 v[10:11], v[60:61], v[46:47], v[10:11] op_sel_hi:[0,1,1]
	v_pk_fma_f32 v[12:13], v[62:63], v[46:47], v[12:13] op_sel_hi:[0,1,1]
	v_pk_fma_f32 v[14:15], v[64:65], v[46:47], v[14:15] op_sel_hi:[0,1,1]
	v_pk_fma_f32 v[16:17], v[66:67], v[46:47], v[16:17] op_sel_hi:[0,1,1]
	v_pk_fma_f32 v[18:19], v[68:69], v[46:47], v[18:19] op_sel_hi:[0,1,1]
	v_pk_fma_f32 v[20:21], v[70:71], v[46:47], v[20:21] op_sel_hi:[0,1,1]
	global_store_dword v154, v54, s[14:15] offset:-4096
	s_waitcnt lgkmcnt(5)
	v_pk_mul_f32 v[38:39], v[6:7], v[80:81] op_sel_hi:[1,0]
	v_pk_mul_f32 v[40:41], v[6:7], v[80:81] op_sel:[0,1] op_sel_hi:[1,1]
	v_pk_fma_f32 v[38:39], v[8:9], v[82:83], v[38:39] op_sel_hi:[1,0,1]
	v_pk_fma_f32 v[40:41], v[8:9], v[82:83], v[40:41] op_sel:[0,1,0] op_sel_hi:[1,1,1]
	s_waitcnt lgkmcnt(3)
	v_pk_fma_f32 v[38:39], v[10:11], v[84:85], v[38:39] op_sel_hi:[1,0,1]
	v_pk_fma_f32 v[40:41], v[10:11], v[84:85], v[40:41] op_sel:[0,1,0] op_sel_hi:[1,1,1]
	v_pk_fma_f32 v[38:39], v[12:13], v[86:87], v[38:39] op_sel_hi:[1,0,1]
	v_pk_fma_f32 v[40:41], v[12:13], v[86:87], v[40:41] op_sel:[0,1,0] op_sel_hi:[1,1,1]
	v_pk_fma_f32 v[38:39], v[14:15], v[88:89], v[38:39] op_sel_hi:[1,0,1]
	v_pk_fma_f32 v[40:41], v[14:15], v[88:89], v[40:41] op_sel:[0,1,0] op_sel_hi:[1,1,1]
	v_pk_fma_f32 v[38:39], v[16:17], v[90:91], v[38:39] op_sel_hi:[1,0,1]
	v_pk_fma_f32 v[40:41], v[16:17], v[90:91], v[40:41] op_sel:[0,1,0] op_sel_hi:[1,1,1]
	s_waitcnt lgkmcnt(0)
	v_pk_fma_f32 v[38:39], v[18:19], v[92:93], v[38:39] op_sel_hi:[1,0,1]
	v_pk_fma_f32 v[40:41], v[18:19], v[92:93], v[40:41] op_sel:[0,1,0] op_sel_hi:[1,1,1]
	v_pk_fma_f32 v[38:39], v[20:21], v[94:95], v[38:39] op_sel_hi:[1,0,1]
	v_pk_fma_f32 v[40:41], v[20:21], v[94:95], v[40:41] op_sel:[0,1,0] op_sel_hi:[1,1,1]
	v_mul_f32_e32 v51, v100, v50
	v_add_f32_dpp v38, v38, v38 row_ror:8 row_mask:0xf bank_mask:0x3 bound_ctrl:1
	v_add_f32_dpp v39, v39, v39 row_ror:8 row_mask:0xf bank_mask:0x3 bound_ctrl:1
	v_add_f32_dpp v38, v40, v40 row_ror:8 row_mask:0xf bank_mask:0xc bound_ctrl:1
	v_add_f32_dpp v39, v41, v41 row_ror:8 row_mask:0xf bank_mask:0xc bound_ctrl:1
	ds_read_b128 v[56:59], v2 offset:6400
	v_add_f32_dpp v38, v38, v38 row_half_mirror row_mask:0xf bank_mask:0x5 bound_ctrl:1
	v_add_f32_dpp v38, v39, v39 row_half_mirror row_mask:0xf bank_mask:0xa bound_ctrl:1
	ds_read_b128 v[60:63], v2 offset:6656
	ds_read_b128 v[64:67], v2 offset:6912
	v_add_f32_dpp v38, v38, v38 quad_perm:[1,0,3,2] row_mask:0xf bank_mask:0xf bound_ctrl:1
	ds_read_b128 v[68:71], v2 offset:7168
	ds_read_b64 v[72:73], v3 offset:14080
	v_add_f32_dpp v38, v38, v38 quad_perm:[2,3,0,1] row_mask:0xf bank_mask:0xf bound_ctrl:1
	ds_read_b128 v[76:79], v1 offset:14688
	v_cmp_gt_f32_e32 vcc, 0x2b8cbccc, v51
	v_fmac_f32_dpp v96, -v38, v51 row_newbcast:0 row_mask:0xf bank_mask:0xf bound_ctrl:1
	v_fmac_f32_dpp v97, -v38, v51 row_newbcast:4 row_mask:0xf bank_mask:0xf bound_ctrl:1
	v_pk_mul_f32 v[44:45], v[96:97], v[100:101] op_sel:[0,1] op_sel_hi:[1,1]
	v_pk_mul_f32 v[48:49], v[44:45], v[102:103] op_sel_hi:[1,0]
	v_rcp_f32_e32 v52, v51
	s_add_u32 s14, s14, 0x1000
	s_addc_u32 s15, s15, 0
	v_fmac_f32_dpp v48, v38, v51 row_newbcast:8 row_mask:0xf bank_mask:0xf bound_ctrl:1
	v_fmac_f32_dpp v49, v38, v51 row_newbcast:12 row_mask:0xf bank_mask:0xf bound_ctrl:1
	s_cbranch_vccnz .Lgd2_rare0_5
.Lgd2_back0_5:
	v_cvt_pk_bf16_f32 v54, v48, v49
	v_pk_mul_f32 v[46:47], v[44:45], v[52:53] op_sel_hi:[1,0]
	v_pk_fma_f32 v[6:7], v[80:81], v[46:47], v[6:7] op_sel_hi:[0,1,1]
	v_pk_fma_f32 v[8:9], v[82:83], v[46:47], v[8:9] op_sel_hi:[0,1,1]
	v_pk_fma_f32 v[10:11], v[84:85], v[46:47], v[10:11] op_sel_hi:[0,1,1]
	v_pk_fma_f32 v[12:13], v[86:87], v[46:47], v[12:13] op_sel_hi:[0,1,1]
	v_pk_fma_f32 v[14:15], v[88:89], v[46:47], v[14:15] op_sel_hi:[0,1,1]
	v_pk_fma_f32 v[16:17], v[90:91], v[46:47], v[16:17] op_sel_hi:[0,1,1]
	v_pk_fma_f32 v[18:19], v[92:93], v[46:47], v[18:19] op_sel_hi:[0,1,1]
	v_pk_fma_f32 v[20:21], v[94:95], v[46:47], v[20:21] op_sel_hi:[0,1,1]
	global_store_dword v154, v54, s[14:15] offset:-4096
	s_waitcnt lgkmcnt(5)
	v_pk_mul_f32 v[38:39], v[6:7], v[56:57] op_sel_hi:[1,0]
	v_pk_mul_f32 v[40:41], v[6:7], v[56:57] op_sel:[0,1] op_sel_hi:[1,1]
	v_pk_fma_f32 v[38:39], v[8:9], v[58:59], v[38:39] op_sel_hi:[1,0,1]
	v_pk_fma_f32 v[40:41], v[8:9], v[58:59], v[40:41] op_sel:[0,1,0] op_sel_hi:[1,1,1]
	s_waitcnt lgkmcnt(3)
	v_pk_fma_f32 v[38:39], v[10:11], v[60:61], v[38:39] op_sel_hi:[1,0,1]
	v_pk_fma_f32 v[40:41], v[10:11], v[60:61], v[40:41] op_sel:[0,1,0] op_sel_hi:[1,1,1]
	v_pk_fma_f32 v[38:39], v[12:13], v[62:63], v[38:39] op_sel_hi:[1,0,1]
	v_pk_fma_f32 v[40:41], v[12:13], v[62:63], v[40:41] op_sel:[0,1,0] op_sel_hi:[1,1,1]
	v_pk_fma_f32 v[38:39], v[14:15], v[64:65], v[38:39] op_sel_hi:[1,0,1]
	v_pk_fma_f32 v[40:41], v[14:15], v[64:65], v[40:41] op_sel:[0,1,0] op_sel_hi:[1,1,1]
	v_pk_fma_f32 v[38:39], v[16:17], v[66:67], v[38:39] op_sel_hi:[1,0,1]
	v_pk_fma_f32 v[40:41], v[16:17], v[66:67], v[40:41] op_sel:[0,1,0] op_sel_hi:[1,1,1]
	s_waitcnt lgkmcnt(0)
	v_pk_fma_f32 v[38:39], v[18:19], v[68:69], v[38:39] op_sel_hi:[1,0,1]
	v_pk_fma_f32 v[40:41], v[18:19], v[68:69], v[40:41] op_sel:[0,1,0] op_sel_hi:[1,1,1]
	v_pk_fma_f32 v[38:39], v[20:21], v[70:71], v[38:39] op_sel_hi:[1,0,1]
	v_pk_fma_f32 v[40:41], v[20:21], v[70:71], v[40:41] op_sel:[0,1,0] op_sel_hi:[1,1,1]
	v_mul_f32_e32 v50, v76, v51
	v_add_f32_dpp v38, v38, v38 row_ror:8 row_mask:0xf bank_mask:0x3 bound_ctrl:1
	v_add_f32_dpp v39, v39, v39 row_ror:8 row_mask:0xf bank_mask:0x3 bound_ctrl:1
	v_add_f32_dpp v38, v40, v40 row_ror:8 row_mask:0xf bank_mask:0xc bound_ctrl:1
	v_add_f32_dpp v39, v41, v41 row_ror:8 row_mask:0xf bank_mask:0xc bound_ctrl:1
	ds_read_b128 v[80:83], v2 offset:7424
	v_add_f32_dpp v38, v38, v38 row_half_mirror row_mask:0xf bank_mask:0x5 bound_ctrl:1
	v_add_f32_dpp v38, v39, v39 row_half_mirror row_mask:0xf bank_mask:0xa bound_ctrl:1
	ds_read_b128 v[84:87], v2 offset:7680
	ds_read_b128 v[88:91], v2 offset:7936
	v_add_f32_dpp v38, v38, v38 quad_perm:[1,0,3,2] row_mask:0xf bank_mask:0xf bound_ctrl:1
	ds_read_b128 v[92:95], v2 offset:8192
	ds_read_b64 v[96:97], v3 offset:14336
	v_add_f32_dpp v38, v38, v38 quad_perm:[2,3,0,1] row_mask:0xf bank_mask:0xf bound_ctrl:1
	ds_read_b128 v[100:103], v1 offset:14704
	v_cmp_gt_f32_e32 vcc, 0x2b8cbccc, v50
	v_fmac_f32_dpp v72, -v38, v50 row_newbcast:0 row_mask:0xf bank_mask:0xf bound_ctrl:1
	v_fmac_f32_dpp v73, -v38, v50 row_newbcast:4 row_mask:0xf bank_mask:0xf bound_ctrl:1
	v_pk_mul_f32 v[44:45], v[72:73], v[76:77] op_sel:[0,1] op_sel_hi:[1,1]
	v_pk_mul_f32 v[48:49], v[44:45], v[78:79] op_sel_hi:[1,0]
	v_rcp_f32_e32 v52, v50
	s_add_u32 s14, s14, 0x1000
	s_addc_u32 s15, s15, 0
	v_fmac_f32_dpp v48, v38, v50 row_newbcast:8 row_mask:0xf bank_mask:0xf bound_ctrl:1
	v_fmac_f32_dpp v49, v38, v50 row_newbcast:12 row_mask:0xf bank_mask:0xf bound_ctrl:1
	s_cbranch_vccnz .Lgd2_rare0_6
.Lgd2_back0_6:
	v_cvt_pk_bf16_f32 v54, v48, v49
	v_pk_mul_f32 v[46:47], v[44:45], v[52:53] op_sel_hi:[1,0]
	v_pk_fma_f32 v[6:7], v[56:57], v[46:47], v[6:7] op_sel_hi:[0,1,1]
	v_pk_fma_f32 v[8:9], v[58:59], v[46:47], v[8:9] op_sel_hi:[0,1,1]
	v_pk_fma_f32 v[10:11], v[60:61], v[46:47], v[10:11] op_sel_hi:[0,1,1]
	v_pk_fma_f32 v[12:13], v[62:63], v[46:47], v[12:13] op_sel_hi:[0,1,1]
	v_pk_fma_f32 v[14:15], v[64:65], v[46:47], v[14:15] op_sel_hi:[0,1,1]
	v_pk_fma_f32 v[16:17], v[66:67], v[46:47], v[16:17] op_sel_hi:[0,1,1]
	v_pk_fma_f32 v[18:19], v[68:69], v[46:47], v[18:19] op_sel_hi:[0,1,1]
	v_pk_fma_f32 v[20:21], v[70:71], v[46:47], v[20:21] op_sel_hi:[0,1,1]
	global_store_dword v154, v54, s[14:15] offset:-4096
	s_waitcnt lgkmcnt(5)
	v_pk_mul_f32 v[38:39], v[6:7], v[80:81] op_sel_hi:[1,0]
	v_pk_mul_f32 v[40:41], v[6:7], v[80:81] op_sel:[0,1] op_sel_hi:[1,1]
	v_pk_fma_f32 v[38:39], v[8:9], v[82:83], v[38:39] op_sel_hi:[1,0,1]
	v_pk_fma_f32 v[40:41], v[8:9], v[82:83], v[40:41] op_sel:[0,1,0] op_sel_hi:[1,1,1]
	s_waitcnt lgkmcnt(3)
	v_pk_fma_f32 v[38:39], v[10:11], v[84:85], v[38:39] op_sel_hi:[1,0,1]
	v_pk_fma_f32 v[40:41], v[10:11], v[84:85], v[40:41] op_sel:[0,1,0] op_sel_hi:[1,1,1]
	v_pk_fma_f32 v[38:39], v[12:13], v[86:87], v[38:39] op_sel_hi:[1,0,1]
	v_pk_fma_f32 v[40:41], v[12:13], v[86:87], v[40:41] op_sel:[0,1,0] op_sel_hi:[1,1,1]
	v_pk_fma_f32 v[38:39], v[14:15], v[88:89], v[38:39] op_sel_hi:[1,0,1]
	v_pk_fma_f32 v[40:41], v[14:15], v[88:89], v[40:41] op_sel:[0,1,0] op_sel_hi:[1,1,1]
	v_pk_fma_f32 v[38:39], v[16:17], v[90:91], v[38:39] op_sel_hi:[1,0,1]
	v_pk_fma_f32 v[40:41], v[16:17], v[90:91], v[40:41] op_sel:[0,1,0] op_sel_hi:[1,1,1]
	s_waitcnt lgkmcnt(0)
	v_pk_fma_f32 v[38:39], v[18:19], v[92:93], v[38:39] op_sel_hi:[1,0,1]
	v_pk_fma_f32 v[40:41], v[18:19], v[92:93], v[40:41] op_sel:[0,1,0] op_sel_hi:[1,1,1]
	v_pk_fma_f32 v[38:39], v[20:21], v[94:95], v[38:39] op_sel_hi:[1,0,1]
	v_pk_fma_f32 v[40:41], v[20:21], v[94:95], v[40:41] op_sel:[0,1,0] op_sel_hi:[1,1,1]
	v_mul_f32_e32 v51, v100, v50
	v_add_f32_dpp v38, v38, v38 row_ror:8 row_mask:0xf bank_mask:0x3 bound_ctrl:1
	v_add_f32_dpp v39, v39, v39 row_ror:8 row_mask:0xf bank_mask:0x3 bound_ctrl:1
	v_add_f32_dpp v38, v40, v40 row_ror:8 row_mask:0xf bank_mask:0xc bound_ctrl:1
	v_add_f32_dpp v39, v41, v41 row_ror:8 row_mask:0xf bank_mask:0xc bound_ctrl:1
	ds_read_b128 v[56:59], v2 offset:16640
	v_add_f32_dpp v38, v38, v38 row_half_mirror row_mask:0xf bank_mask:0x5 bound_ctrl:1
	v_add_f32_dpp v38, v39, v39 row_half_mirror row_mask:0xf bank_mask:0xa bound_ctrl:1
	ds_read_b128 v[60:63], v2 offset:16896
	ds_read_b128 v[64:67], v2 offset:17152
	v_add_f32_dpp v38, v38, v38 quad_perm:[1,0,3,2] row_mask:0xf bank_mask:0xf bound_ctrl:1
	ds_read_b128 v[68:71], v2 offset:17408
	ds_read_b64 v[72:73], v3 offset:28928
	v_add_f32_dpp v38, v38, v38 quad_perm:[2,3,0,1] row_mask:0xf bank_mask:0xf bound_ctrl:1
	ds_read_b128 v[76:79], v1 offset:30976
	v_cmp_gt_f32_e32 vcc, 0x2b8cbccc, v51
	v_fmac_f32_dpp v96, -v38, v51 row_newbcast:0 row_mask:0xf bank_mask:0xf bound_ctrl:1
	v_fmac_f32_dpp v97, -v38, v51 row_newbcast:4 row_mask:0xf bank_mask:0xf bound_ctrl:1
	v_pk_mul_f32 v[44:45], v[96:97], v[100:101] op_sel:[0,1] op_sel_hi:[1,1]
	v_pk_mul_f32 v[48:49], v[44:45], v[102:103] op_sel_hi:[1,0]
	v_rcp_f32_e32 v52, v51
	s_add_u32 s14, s14, 0x1000
	s_addc_u32 s15, s15, 0
	v_fmac_f32_dpp v48, v38, v51 row_newbcast:8 row_mask:0xf bank_mask:0xf bound_ctrl:1
	v_fmac_f32_dpp v49, v38, v51 row_newbcast:12 row_mask:0xf bank_mask:0xf bound_ctrl:1
	s_cbranch_vccnz .Lgd2_rare0_7
.Lgd2_back0_7:
	v_cvt_pk_bf16_f32 v54, v48, v49
	v_pk_mul_f32 v[46:47], v[44:45], v[52:53] op_sel_hi:[1,0]
	v_pk_fma_f32 v[6:7], v[80:81], v[46:47], v[6:7] op_sel_hi:[0,1,1]
	v_pk_fma_f32 v[8:9], v[82:83], v[46:47], v[8:9] op_sel_hi:[0,1,1]
	v_pk_fma_f32 v[10:11], v[84:85], v[46:47], v[10:11] op_sel_hi:[0,1,1]
	v_pk_fma_f32 v[12:13], v[86:87], v[46:47], v[12:13] op_sel_hi:[0,1,1]
	v_pk_fma_f32 v[14:15], v[88:89], v[46:47], v[14:15] op_sel_hi:[0,1,1]
	v_pk_fma_f32 v[16:17], v[90:91], v[46:47], v[16:17] op_sel_hi:[0,1,1]
	v_pk_fma_f32 v[18:19], v[92:93], v[46:47], v[18:19] op_sel_hi:[0,1,1]
	v_pk_fma_f32 v[20:21], v[94:95], v[46:47], v[20:21] op_sel_hi:[0,1,1]
	global_store_dword v154, v54, s[14:15] offset:-4096
	s_waitcnt vmcnt(8)
	v_lshlrev_b32_e32 v116, 16, v108
	v_lshlrev_b32_e32 v117, 16, v109
	v_and_b32_e32 v118, s17, v108
	v_and_b32_e32 v119, s17, v109
	v_lshlrev_b32_e32 v120, 16, v110
	v_and_b32_e32 v121, s17, v110
	v_lshlrev_b32_e32 v122, 16, v111
	v_and_b32_e32 v123, s17, v111
	v_lshlrev_b32_e32 v124, 16, v112
	v_and_b32_e32 v125, s17, v112
	ds_write_b128 v32, v[116:119] offset:33024
	ds_write_b64 v33, v[120:121] offset:33024
	ds_write_b64 v34, v[122:123] offset:33024
	ds_write_b64 v34, v[124:125] offset:33152
	ds_write_b32 v35, v113 offset:33024
	s_add_i32 s16, s16, 8
	s_waitcnt lgkmcnt(0)
	s_barrier
	s_cmpk_lt_u32 s16, 0x800
	s_cbranch_scc0 .Lgd2_done
	global_load_dword v108, v36, s[8:9]
	global_load_dword v109, v36, s[8:9] offset:-2048
	global_load_dword v111, v104, s[8:9] offset:2048
	global_load_dword v110, v37, s[10:11]
	global_load_dword v112, v105, s[10:11]
	global_load_dword v113, v106, s[12:13]
	s_add_u32 s8, s8, 0xc000
	s_addc_u32 s9, s9, 0
	s_add_u32 s10, s10, 0x20000
	s_addc_u32 s11, s11, 0
	s_add_u32 s12, s12, 0x400
	s_addc_u32 s13, s13, 0
	s_waitcnt lgkmcnt(5)
	v_pk_mul_f32 v[38:39], v[6:7], v[56:57] op_sel_hi:[1,0]
	v_pk_mul_f32 v[40:41], v[6:7], v[56:57] op_sel:[0,1] op_sel_hi:[1,1]
	v_pk_fma_f32 v[38:39], v[8:9], v[58:59], v[38:39] op_sel_hi:[1,0,1]
	v_pk_fma_f32 v[40:41], v[8:9], v[58:59], v[40:41] op_sel:[0,1,0] op_sel_hi:[1,1,1]
	s_waitcnt lgkmcnt(3)
	v_pk_fma_f32 v[38:39], v[10:11], v[60:61], v[38:39] op_sel_hi:[1,0,1]
	v_pk_fma_f32 v[40:41], v[10:11], v[60:61], v[40:41] op_sel:[0,1,0] op_sel_hi:[1,1,1]
	v_pk_fma_f32 v[38:39], v[12:13], v[62:63], v[38:39] op_sel_hi:[1,0,1]
	v_pk_fma_f32 v[40:41], v[12:13], v[62:63], v[40:41] op_sel:[0,1,0] op_sel_hi:[1,1,1]
	v_pk_fma_f32 v[38:39], v[14:15], v[64:65], v[38:39] op_sel_hi:[1,0,1]
	v_pk_fma_f32 v[40:41], v[14:15], v[64:65], v[40:41] op_sel:[0,1,0] op_sel_hi:[1,1,1]
	v_pk_fma_f32 v[38:39], v[16:17], v[66:67], v[38:39] op_sel_hi:[1,0,1]
	v_pk_fma_f32 v[40:41], v[16:17], v[66:67], v[40:41] op_sel:[0,1,0] op_sel_hi:[1,1,1]
	s_waitcnt lgkmcnt(0)
	v_pk_fma_f32 v[38:39], v[18:19], v[68:69], v[38:39] op_sel_hi:[1,0,1]
	v_pk_fma_f32 v[40:41], v[18:19], v[68:69], v[40:41] op_sel:[0,1,0] op_sel_hi:[1,1,1]
	v_pk_fma_f32 v[38:39], v[20:21], v[70:71], v[38:39] op_sel_hi:[1,0,1]
	v_pk_fma_f32 v[40:41], v[20:21], v[70:71], v[40:41] op_sel:[0,1,0] op_sel_hi:[1,1,1]
	v_mul_f32_e32 v50, v76, v51
	v_add_f32_dpp v38, v38, v38 row_ror:8 row_mask:0xf bank_mask:0x3 bound_ctrl:1
	v_add_f32_dpp v39, v39, v39 row_ror:8 row_mask:0xf bank_mask:0x3 bound_ctrl:1
	v_add_f32_dpp v38, v40, v40 row_ror:8 row_mask:0xf bank_mask:0xc bound_ctrl:1
	v_add_f32_dpp v39, v41, v41 row_ror:8 row_mask:0xf bank_mask:0xc bound_ctrl:1
	ds_read_b128 v[80:83], v2 offset:17664
	v_add_f32_dpp v38, v38, v38 row_half_mirror row_mask:0xf bank_mask:0x5 bound_ctrl:1
	v_add_f32_dpp v38, v39, v39 row_half_mirror row_mask:0xf bank_mask:0xa bound_ctrl:1
	ds_read_b128 v[84:87], v2 offset:17920
	ds_read_b128 v[88:91], v2 offset:18176
	v_add_f32_dpp v38, v38, v38 quad_perm:[1,0,3,2] row_mask:0xf bank_mask:0xf bound_ctrl:1
	ds_read_b128 v[92:95], v2 offset:18432
	ds_read_b64 v[96:97], v3 offset:29184
	v_add_f32_dpp v38, v38, v38 quad_perm:[2,3,0,1] row_mask:0xf bank_mask:0xf bound_ctrl:1
	ds_read_b128 v[100:103], v1 offset:30992
	v_cmp_gt_f32_e32 vcc, 0x2b8cbccc, v50
	v_fmac_f32_dpp v72, -v38, v50 row_newbcast:0 row_mask:0xf bank_mask:0xf bound_ctrl:1
	v_fmac_f32_dpp v73, -v38, v50 row_newbcast:4 row_mask:0xf bank_mask:0xf bound_ctrl:1
	v_pk_mul_f32 v[44:45], v[72:73], v[76:77] op_sel:[0,1] op_sel_hi:[1,1]
	v_pk_mul_f32 v[48:49], v[44:45], v[78:79] op_sel_hi:[1,0]
	v_rcp_f32_e32 v52, v50
	s_add_u32 s14, s14, 0x1000
	s_addc_u32 s15, s15, 0
	v_fmac_f32_dpp v48, v38, v50 row_newbcast:8 row_mask:0xf bank_mask:0xf bound_ctrl:1
	v_fmac_f32_dpp v49, v38, v50 row_newbcast:12 row_mask:0xf bank_mask:0xf bound_ctrl:1
	s_cbranch_vccnz .Lgd2_rare1_0
.Lgd2_back1_0:
	v_cvt_pk_bf16_f32 v54, v48, v49
	v_pk_mul_f32 v[46:47], v[44:45], v[52:53] op_sel_hi:[1,0]
	v_pk_fma_f32 v[6:7], v[56:57], v[46:47], v[6:7] op_sel_hi:[0,1,1]
	v_pk_fma_f32 v[8:9], v[58:59], v[46:47], v[8:9] op_sel_hi:[0,1,1]
	v_pk_fma_f32 v[10:11], v[60:61], v[46:47], v[10:11] op_sel_hi:[0,1,1]
	v_pk_fma_f32 v[12:13], v[62:63], v[46:47], v[12:13] op_sel_hi:[0,1,1]
	v_pk_fma_f32 v[14:15], v[64:65], v[46:47], v[14:15] op_sel_hi:[0,1,1]
	v_pk_fma_f32 v[16:17], v[66:67], v[46:47], v[16:17] op_sel_hi:[0,1,1]
	v_pk_fma_f32 v[18:19], v[68:69], v[46:47], v[18:19] op_sel_hi:[0,1,1]
	v_pk_fma_f32 v[20:21], v[70:71], v[46:47], v[20:21] op_sel_hi:[0,1,1]
	global_store_dword v154, v54, s[14:15] offset:-4096
	s_waitcnt lgkmcnt(5)
	v_pk_mul_f32 v[38:39], v[6:7], v[80:81] op_sel_hi:[1,0]
	v_pk_mul_f32 v[40:41], v[6:7], v[80:81] op_sel:[0,1] op_sel_hi:[1,1]
	v_pk_fma_f32 v[38:39], v[8:9], v[82:83], v[38:39] op_sel_hi:[1,0,1]
	v_pk_fma_f32 v[40:41], v[8:9], v[82:83], v[40:41] op_sel:[0,1,0] op_sel_hi:[1,1,1]
	s_waitcnt lgkmcnt(3)
	v_pk_fma_f32 v[38:39], v[10:11], v[84:85], v[38:39] op_sel_hi:[1,0,1]
	v_pk_fma_f32 v[40:41], v[10:11], v[84:85], v[40:41] op_sel:[0,1,0] op_sel_hi:[1,1,1]
	v_pk_fma_f32 v[38:39], v[12:13], v[86:87], v[38:39] op_sel_hi:[1,0,1]
	v_pk_fma_f32 v[40:41], v[12:13], v[86:87], v[40:41] op_sel:[0,1,0] op_sel_hi:[1,1,1]
	v_pk_fma_f32 v[38:39], v[14:15], v[88:89], v[38:39] op_sel_hi:[1,0,1]
	v_pk_fma_f32 v[40:41], v[14:15], v[88:89], v[40:41] op_sel:[0,1,0] op_sel_hi:[1,1,1]
	v_pk_fma_f32 v[38:39], v[16:17], v[90:91], v[38:39] op_sel_hi:[1,0,1]
	v_pk_fma_f32 v[40:41], v[16:17], v[90:91], v[40:41] op_sel:[0,1,0] op_sel_hi:[1,1,1]
	s_waitcnt lgkmcnt(0)
	v_pk_fma_f32 v[38:39], v[18:19], v[92:93], v[38:39] op_sel_hi:[1,0,1]
	v_pk_fma_f32 v[40:41], v[18:19], v[92:93], v[40:41] op_sel:[0,1,0] op_sel_hi:[1,1,1]
	v_pk_fma_f32 v[38:39], v[20:21], v[94:95], v[38:39] op_sel_hi:[1,0,1]
	v_pk_fma_f32 v[40:41], v[20:21], v[94:95], v[40:41] op_sel:[0,1,0] op_sel_hi:[1,1,1]
	v_mul_f32_e32 v51, v100, v50
	v_add_f32_dpp v38, v38, v38 row_ror:8 row_mask:0xf bank_mask:0x3 bound_ctrl:1
	v_add_f32_dpp v39, v39, v39 row_ror:8 row_mask:0xf bank_mask:0x3 bound_ctrl:1
	v_add_f32_dpp v38, v40, v40 row_ror:8 row_mask:0xf bank_mask:0xc bound_ctrl:1
	v_add_f32_dpp v39, v41, v41 row_ror:8 row_mask:0xf bank_mask:0xc bound_ctrl:1
	ds_read_b128 v[56:59], v2 offset:18688
	v_add_f32_dpp v38, v38, v38 row_half_mirror row_mask:0xf bank_mask:0x5 bound_ctrl:1
	v_add_f32_dpp v38, v39, v39 row_half_mirror row_mask:0xf bank_mask:0xa bound_ctrl:1
	ds_read_b128 v[60:63], v2 offset:18944
	ds_read_b128 v[64:67], v2 offset:19200
	v_add_f32_dpp v38, v38, v38 quad_perm:[1,0,3,2] row_mask:0xf bank_mask:0xf bound_ctrl:1
	ds_read_b128 v[68:71], v2 offset:19456
	ds_read_b64 v[72:73], v3 offset:29440
	v_add_f32_dpp v38, v38, v38 quad_perm:[2,3,0,1] row_mask:0xf bank_mask:0xf bound_ctrl:1
	ds_read_b128 v[76:79], v1 offset:31008
	v_cmp_gt_f32_e32 vcc, 0x2b8cbccc, v51
	v_fmac_f32_dpp v96, -v38, v51 row_newbcast:0 row_mask:0xf bank_mask:0xf bound_ctrl:1
	v_fmac_f32_dpp v97, -v38, v51 row_newbcast:4 row_mask:0xf bank_mask:0xf bound_ctrl:1
	v_pk_mul_f32 v[44:45], v[96:97], v[100:101] op_sel:[0,1] op_sel_hi:[1,1]
	v_pk_mul_f32 v[48:49], v[44:45], v[102:103] op_sel_hi:[1,0]
	v_rcp_f32_e32 v52, v51
	s_add_u32 s14, s14, 0x1000
	s_addc_u32 s15, s15, 0
	v_fmac_f32_dpp v48, v38, v51 row_newbcast:8 row_mask:0xf bank_mask:0xf bound_ctrl:1
	v_fmac_f32_dpp v49, v38, v51 row_newbcast:12 row_mask:0xf bank_mask:0xf bound_ctrl:1
	s_cbranch_vccnz .Lgd2_rare1_1
.Lgd2_back1_1:
	v_cvt_pk_bf16_f32 v54, v48, v49
	v_pk_mul_f32 v[46:47], v[44:45], v[52:53] op_sel_hi:[1,0]
	v_pk_fma_f32 v[6:7], v[80:81], v[46:47], v[6:7] op_sel_hi:[0,1,1]
	v_pk_fma_f32 v[8:9], v[82:83], v[46:47], v[8:9] op_sel_hi:[0,1,1]
	v_pk_fma_f32 v[10:11], v[84:85], v[46:47], v[10:11] op_sel_hi:[0,1,1]
	v_pk_fma_f32 v[12:13], v[86:87], v[46:47], v[12:13] op_sel_hi:[0,1,1]
	v_pk_fma_f32 v[14:15], v[88:89], v[46:47], v[14:15] op_sel_hi:[0,1,1]
	v_pk_fma_f32 v[16:17], v[90:91], v[46:47], v[16:17] op_sel_hi:[0,1,1]
	v_pk_fma_f32 v[18:19], v[92:93], v[46:47], v[18:19] op_sel_hi:[0,1,1]
	v_pk_fma_f32 v[20:21], v[94:95], v[46:47], v[20:21] op_sel_hi:[0,1,1]
	global_store_dword v154, v54, s[14:15] offset:-4096
	s_waitcnt lgkmcnt(5)
	v_pk_mul_f32 v[38:39], v[6:7], v[56:57] op_sel_hi:[1,0]
	v_pk_mul_f32 v[40:41], v[6:7], v[56:57] op_sel:[0,1] op_sel_hi:[1,1]
	v_pk_fma_f32 v[38:39], v[8:9], v[58:59], v[38:39] op_sel_hi:[1,0,1]
	v_pk_fma_f32 v[40:41], v[8:9], v[58:59], v[40:41] op_sel:[0,1,0] op_sel_hi:[1,1,1]
	s_waitcnt lgkmcnt(3)
	v_pk_fma_f32 v[38:39], v[10:11], v[60:61], v[38:39] op_sel_hi:[1,0,1]
	v_pk_fma_f32 v[40:41], v[10:11], v[60:61], v[40:41] op_sel:[0,1,0] op_sel_hi:[1,1,1]
	v_pk_fma_f32 v[38:39], v[12:13], v[62:63], v[38:39] op_sel_hi:[1,0,1]
	v_pk_fma_f32 v[40:41], v[12:13], v[62:63], v[40:41] op_sel:[0,1,0] op_sel_hi:[1,1,1]
	v_pk_fma_f32 v[38:39], v[14:15], v[64:65], v[38:39] op_sel_hi:[1,0,1]
	v_pk_fma_f32 v[40:41], v[14:15], v[64:65], v[40:41] op_sel:[0,1,0] op_sel_hi:[1,1,1]
	v_pk_fma_f32 v[38:39], v[16:17], v[66:67], v[38:39] op_sel_hi:[1,0,1]
	v_pk_fma_f32 v[40:41], v[16:17], v[66:67], v[40:41] op_sel:[0,1,0] op_sel_hi:[1,1,1]
	s_waitcnt lgkmcnt(0)
	v_pk_fma_f32 v[38:39], v[18:19], v[68:69], v[38:39] op_sel_hi:[1,0,1]
	v_pk_fma_f32 v[40:41], v[18:19], v[68:69], v[40:41] op_sel:[0,1,0] op_sel_hi:[1,1,1]
	v_pk_fma_f32 v[38:39], v[20:21], v[70:71], v[38:39] op_sel_hi:[1,0,1]
	v_pk_fma_f32 v[40:41], v[20:21], v[70:71], v[40:41] op_sel:[0,1,0] op_sel_hi:[1,1,1]
	v_mul_f32_e32 v50, v76, v51
	v_add_f32_dpp v38, v38, v38 row_ror:8 row_mask:0xf bank_mask:0x3 bound_ctrl:1
	v_add_f32_dpp v39, v39, v39 row_ror:8 row_mask:0xf bank_mask:0x3 bound_ctrl:1
	v_add_f32_dpp v38, v40, v40 row_ror:8 row_mask:0xf bank_mask:0xc bound_ctrl:1
	v_add_f32_dpp v39, v41, v41 row_ror:8 row_mask:0xf bank_mask:0xc bound_ctrl:1
	ds_read_b128 v[80:83], v2 offset:19712
	v_add_f32_dpp v38, v38, v38 row_half_mirror row_mask:0xf bank_mask:0x5 bound_ctrl:1
	v_add_f32_dpp v38, v39, v39 row_half_mirror row_mask:0xf bank_mask:0xa bound_ctrl:1
	ds_read_b128 v[84:87], v2 offset:19968
	ds_read_b128 v[88:91], v2 offset:20224
	v_add_f32_dpp v38, v38, v38 quad_perm:[1,0,3,2] row_mask:0xf bank_mask:0xf bound_ctrl:1
	ds_read_b128 v[92:95], v2 offset:20480
	ds_read_b64 v[96:97], v3 offset:29696
	v_add_f32_dpp v38, v38, v38 quad_perm:[2,3,0,1] row_mask:0xf bank_mask:0xf bound_ctrl:1
	ds_read_b128 v[100:103], v1 offset:31024
	v_cmp_gt_f32_e32 vcc, 0x2b8cbccc, v50
	v_fmac_f32_dpp v72, -v38, v50 row_newbcast:0 row_mask:0xf bank_mask:0xf bound_ctrl:1
	v_fmac_f32_dpp v73, -v38, v50 row_newbcast:4 row_mask:0xf bank_mask:0xf bound_ctrl:1
	v_pk_mul_f32 v[44:45], v[72:73], v[76:77] op_sel:[0,1] op_sel_hi:[1,1]
	v_pk_mul_f32 v[48:49], v[44:45], v[78:79] op_sel_hi:[1,0]
	v_rcp_f32_e32 v52, v50
	s_add_u32 s14, s14, 0x1000
	s_addc_u32 s15, s15, 0
	v_fmac_f32_dpp v48, v38, v50 row_newbcast:8 row_mask:0xf bank_mask:0xf bound_ctrl:1
	v_fmac_f32_dpp v49, v38, v50 row_newbcast:12 row_mask:0xf bank_mask:0xf bound_ctrl:1
	s_cbranch_vccnz .Lgd2_rare1_2
.Lgd2_back1_2:
	v_cvt_pk_bf16_f32 v54, v48, v49
	v_pk_mul_f32 v[46:47], v[44:45], v[52:53] op_sel_hi:[1,0]
	v_pk_fma_f32 v[6:7], v[56:57], v[46:47], v[6:7] op_sel_hi:[0,1,1]
	v_pk_fma_f32 v[8:9], v[58:59], v[46:47], v[8:9] op_sel_hi:[0,1,1]
	v_pk_fma_f32 v[10:11], v[60:61], v[46:47], v[10:11] op_sel_hi:[0,1,1]
	v_pk_fma_f32 v[12:13], v[62:63], v[46:47], v[12:13] op_sel_hi:[0,1,1]
	v_pk_fma_f32 v[14:15], v[64:65], v[46:47], v[14:15] op_sel_hi:[0,1,1]
	v_pk_fma_f32 v[16:17], v[66:67], v[46:47], v[16:17] op_sel_hi:[0,1,1]
	v_pk_fma_f32 v[18:19], v[68:69], v[46:47], v[18:19] op_sel_hi:[0,1,1]
	v_pk_fma_f32 v[20:21], v[70:71], v[46:47], v[20:21] op_sel_hi:[0,1,1]
	global_store_dword v154, v54, s[14:15] offset:-4096
	s_waitcnt lgkmcnt(5)
	v_pk_mul_f32 v[38:39], v[6:7], v[80:81] op_sel_hi:[1,0]
	v_pk_mul_f32 v[40:41], v[6:7], v[80:81] op_sel:[0,1] op_sel_hi:[1,1]
	v_pk_fma_f32 v[38:39], v[8:9], v[82:83], v[38:39] op_sel_hi:[1,0,1]
	v_pk_fma_f32 v[40:41], v[8:9], v[82:83], v[40:41] op_sel:[0,1,0] op_sel_hi:[1,1,1]
	s_waitcnt lgkmcnt(3)
	v_pk_fma_f32 v[38:39], v[10:11], v[84:85], v[38:39] op_sel_hi:[1,0,1]
	v_pk_fma_f32 v[40:41], v[10:11], v[84:85], v[40:41] op_sel:[0,1,0] op_sel_hi:[1,1,1]
	v_pk_fma_f32 v[38:39], v[12:13], v[86:87], v[38:39] op_sel_hi:[1,0,1]
	v_pk_fma_f32 v[40:41], v[12:13], v[86:87], v[40:41] op_sel:[0,1,0] op_sel_hi:[1,1,1]
	v_pk_fma_f32 v[38:39], v[14:15], v[88:89], v[38:39] op_sel_hi:[1,0,1]
	v_pk_fma_f32 v[40:41], v[14:15], v[88:89], v[40:41] op_sel:[0,1,0] op_sel_hi:[1,1,1]
	v_pk_fma_f32 v[38:39], v[16:17], v[90:91], v[38:39] op_sel_hi:[1,0,1]
	v_pk_fma_f32 v[40:41], v[16:17], v[90:91], v[40:41] op_sel:[0,1,0] op_sel_hi:[1,1,1]
	s_waitcnt lgkmcnt(0)
	v_pk_fma_f32 v[38:39], v[18:19], v[92:93], v[38:39] op_sel_hi:[1,0,1]
	v_pk_fma_f32 v[40:41], v[18:19], v[92:93], v[40:41] op_sel:[0,1,0] op_sel_hi:[1,1,1]
	v_pk_fma_f32 v[38:39], v[20:21], v[94:95], v[38:39] op_sel_hi:[1,0,1]
	v_pk_fma_f32 v[40:41], v[20:21], v[94:95], v[40:41] op_sel:[0,1,0] op_sel_hi:[1,1,1]
	v_mul_f32_e32 v51, v100, v50
	v_add_f32_dpp v38, v38, v38 row_ror:8 row_mask:0xf bank_mask:0x3 bound_ctrl:1
	v_add_f32_dpp v39, v39, v39 row_ror:8 row_mask:0xf bank_mask:0x3 bound_ctrl:1
	v_add_f32_dpp v38, v40, v40 row_ror:8 row_mask:0xf bank_mask:0xc bound_ctrl:1
	v_add_f32_dpp v39, v41, v41 row_ror:8 row_mask:0xf bank_mask:0xc bound_ctrl:1
	ds_read_b128 v[56:59], v2 offset:20736
	v_add_f32_dpp v38, v38, v38 row_half_mirror row_mask:0xf bank_mask:0x5 bound_ctrl:1
	v_add_f32_dpp v38, v39, v39 row_half_mirror row_mask:0xf bank_mask:0xa bound_ctrl:1
	ds_read_b128 v[60:63], v2 offset:20992
	ds_read_b128 v[64:67], v2 offset:21248
	v_add_f32_dpp v38, v38, v38 quad_perm:[1,0,3,2] row_mask:0xf bank_mask:0xf bound_ctrl:1
	ds_read_b128 v[68:71], v2 offset:21504
	ds_read_b64 v[72:73], v3 offset:29952
	v_add_f32_dpp v38, v38, v38 quad_perm:[2,3,0,1] row_mask:0xf bank_mask:0xf bound_ctrl:1
	ds_read_b128 v[76:79], v1 offset:31040
	v_cmp_gt_f32_e32 vcc, 0x2b8cbccc, v51
	v_fmac_f32_dpp v96, -v38, v51 row_newbcast:0 row_mask:0xf bank_mask:0xf bound_ctrl:1
	v_fmac_f32_dpp v97, -v38, v51 row_newbcast:4 row_mask:0xf bank_mask:0xf bound_ctrl:1
	v_pk_mul_f32 v[44:45], v[96:97], v[100:101] op_sel:[0,1] op_sel_hi:[1,1]
	v_pk_mul_f32 v[48:49], v[44:45], v[102:103] op_sel_hi:[1,0]
	v_rcp_f32_e32 v52, v51
	s_add_u32 s14, s14, 0x1000
	s_addc_u32 s15, s15, 0
	v_fmac_f32_dpp v48, v38, v51 row_newbcast:8 row_mask:0xf bank_mask:0xf bound_ctrl:1
	v_fmac_f32_dpp v49, v38, v51 row_newbcast:12 row_mask:0xf bank_mask:0xf bound_ctrl:1
	s_cbranch_vccnz .Lgd2_rare1_3
.Lgd2_back1_3:
	v_cvt_pk_bf16_f32 v54, v48, v49
	v_pk_mul_f32 v[46:47], v[44:45], v[52:53] op_sel_hi:[1,0]
	v_pk_fma_f32 v[6:7], v[80:81], v[46:47], v[6:7] op_sel_hi:[0,1,1]
	v_pk_fma_f32 v[8:9], v[82:83], v[46:47], v[8:9] op_sel_hi:[0,1,1]
	v_pk_fma_f32 v[10:11], v[84:85], v[46:47], v[10:11] op_sel_hi:[0,1,1]
	v_pk_fma_f32 v[12:13], v[86:87], v[46:47], v[12:13] op_sel_hi:[0,1,1]
	v_pk_fma_f32 v[14:15], v[88:89], v[46:47], v[14:15] op_sel_hi:[0,1,1]
	v_pk_fma_f32 v[16:17], v[90:91], v[46:47], v[16:17] op_sel_hi:[0,1,1]
	v_pk_fma_f32 v[18:19], v[92:93], v[46:47], v[18:19] op_sel_hi:[0,1,1]
	v_pk_fma_f32 v[20:21], v[94:95], v[46:47], v[20:21] op_sel_hi:[0,1,1]
	global_store_dword v154, v54, s[14:15] offset:-4096
	s_waitcnt lgkmcnt(5)
	v_pk_mul_f32 v[38:39], v[6:7], v[56:57] op_sel_hi:[1,0]
	v_pk_mul_f32 v[40:41], v[6:7], v[56:57] op_sel:[0,1] op_sel_hi:[1,1]
	v_pk_fma_f32 v[38:39], v[8:9], v[58:59], v[38:39] op_sel_hi:[1,0,1]
	v_pk_fma_f32 v[40:41], v[8:9], v[58:59], v[40:41] op_sel:[0,1,0] op_sel_hi:[1,1,1]
	s_waitcnt lgkmcnt(3)
	v_pk_fma_f32 v[38:39], v[10:11], v[60:61], v[38:39] op_sel_hi:[1,0,1]
	v_pk_fma_f32 v[40:41], v[10:11], v[60:61], v[40:41] op_sel:[0,1,0] op_sel_hi:[1,1,1]
	v_pk_fma_f32 v[38:39], v[12:13], v[62:63], v[38:39] op_sel_hi:[1,0,1]
	v_pk_fma_f32 v[40:41], v[12:13], v[62:63], v[40:41] op_sel:[0,1,0] op_sel_hi:[1,1,1]
	v_pk_fma_f32 v[38:39], v[14:15], v[64:65], v[38:39] op_sel_hi:[1,0,1]
	v_pk_fma_f32 v[40:41], v[14:15], v[64:65], v[40:41] op_sel:[0,1,0] op_sel_hi:[1,1,1]
	v_pk_fma_f32 v[38:39], v[16:17], v[66:67], v[38:39] op_sel_hi:[1,0,1]
	v_pk_fma_f32 v[40:41], v[16:17], v[66:67], v[40:41] op_sel:[0,1,0] op_sel_hi:[1,1,1]
	s_waitcnt lgkmcnt(0)
	v_pk_fma_f32 v[38:39], v[18:19], v[68:69], v[38:39] op_sel_hi:[1,0,1]
	v_pk_fma_f32 v[40:41], v[18:19], v[68:69], v[40:41] op_sel:[0,1,0] op_sel_hi:[1,1,1]
	v_pk_fma_f32 v[38:39], v[20:21], v[70:71], v[38:39] op_sel_hi:[1,0,1]
	v_pk_fma_f32 v[40:41], v[20:21], v[70:71], v[40:41] op_sel:[0,1,0] op_sel_hi:[1,1,1]
	v_mul_f32_e32 v50, v76, v51
	v_add_f32_dpp v38, v38, v38 row_ror:8 row_mask:0xf bank_mask:0x3 bound_ctrl:1
	v_add_f32_dpp v39, v39, v39 row_ror:8 row_mask:0xf bank_mask:0x3 bound_ctrl:1
	v_add_f32_dpp v38, v40, v40 row_ror:8 row_mask:0xf bank_mask:0xc bound_ctrl:1
	v_add_f32_dpp v39, v41, v41 row_ror:8 row_mask:0xf bank_mask:0xc bound_ctrl:1
	ds_read_b128 v[80:83], v2 offset:21760
	v_add_f32_dpp v38, v38, v38 row_half_mirror row_mask:0xf bank_mask:0x5 bound_ctrl:1
	v_add_f32_dpp v38, v39, v39 row_half_mirror row_mask:0xf bank_mask:0xa bound_ctrl:1
	ds_read_b128 v[84:87], v2 offset:22016
	ds_read_b128 v[88:91], v2 offset:22272
	v_add_f32_dpp v38, v38, v38 quad_perm:[1,0,3,2] row_mask:0xf bank_mask:0xf bound_ctrl:1
	ds_read_b128 v[92:95], v2 offset:22528
	ds_read_b64 v[96:97], v3 offset:30208
	v_add_f32_dpp v38, v38, v38 quad_perm:[2,3,0,1] row_mask:0xf bank_mask:0xf bound_ctrl:1
	ds_read_b128 v[100:103], v1 offset:31056
	v_cmp_gt_f32_e32 vcc, 0x2b8cbccc, v50
	v_fmac_f32_dpp v72, -v38, v50 row_newbcast:0 row_mask:0xf bank_mask:0xf bound_ctrl:1
	v_fmac_f32_dpp v73, -v38, v50 row_newbcast:4 row_mask:0xf bank_mask:0xf bound_ctrl:1
	v_pk_mul_f32 v[44:45], v[72:73], v[76:77] op_sel:[0,1] op_sel_hi:[1,1]
	v_pk_mul_f32 v[48:49], v[44:45], v[78:79] op_sel_hi:[1,0]
	v_rcp_f32_e32 v52, v50
	s_add_u32 s14, s14, 0x1000
	s_addc_u32 s15, s15, 0
	v_fmac_f32_dpp v48, v38, v50 row_newbcast:8 row_mask:0xf bank_mask:0xf bound_ctrl:1
	v_fmac_f32_dpp v49, v38, v50 row_newbcast:12 row_mask:0xf bank_mask:0xf bound_ctrl:1
	s_cbranch_vccnz .Lgd2_rare1_4
.Lgd2_back1_4:
	v_cvt_pk_bf16_f32 v54, v48, v49
	v_pk_mul_f32 v[46:47], v[44:45], v[52:53] op_sel_hi:[1,0]
	v_pk_fma_f32 v[6:7], v[56:57], v[46:47], v[6:7] op_sel_hi:[0,1,1]
	v_pk_fma_f32 v[8:9], v[58:59], v[46:47], v[8:9] op_sel_hi:[0,1,1]
	v_pk_fma_f32 v[10:11], v[60:61], v[46:47], v[10:11] op_sel_hi:[0,1,1]
	v_pk_fma_f32 v[12:13], v[62:63], v[46:47], v[12:13] op_sel_hi:[0,1,1]
	v_pk_fma_f32 v[14:15], v[64:65], v[46:47], v[14:15] op_sel_hi:[0,1,1]
	v_pk_fma_f32 v[16:17], v[66:67], v[46:47], v[16:17] op_sel_hi:[0,1,1]
	v_pk_fma_f32 v[18:19], v[68:69], v[46:47], v[18:19] op_sel_hi:[0,1,1]
	v_pk_fma_f32 v[20:21], v[70:71], v[46:47], v[20:21] op_sel_hi:[0,1,1]
	global_store_dword v154, v54, s[14:15] offset:-4096
	s_waitcnt lgkmcnt(5)
	v_pk_mul_f32 v[38:39], v[6:7], v[80:81] op_sel_hi:[1,0]
	v_pk_mul_f32 v[40:41], v[6:7], v[80:81] op_sel:[0,1] op_sel_hi:[1,1]
	v_pk_fma_f32 v[38:39], v[8:9], v[82:83], v[38:39] op_sel_hi:[1,0,1]
	v_pk_fma_f32 v[40:41], v[8:9], v[82:83], v[40:41] op_sel:[0,1,0] op_sel_hi:[1,1,1]
	s_waitcnt lgkmcnt(3)
	v_pk_fma_f32 v[38:39], v[10:11], v[84:85], v[38:39] op_sel_hi:[1,0,1]
	v_pk_fma_f32 v[40:41], v[10:11], v[84:85], v[40:41] op_sel:[0,1,0] op_sel_hi:[1,1,1]
	v_pk_fma_f32 v[38:39], v[12:13], v[86:87], v[38:39] op_sel_hi:[1,0,1]
	v_pk_fma_f32 v[40:41], v[12:13], v[86:87], v[40:41] op_sel:[0,1,0] op_sel_hi:[1,1,1]
	v_pk_fma_f32 v[38:39], v[14:15], v[88:89], v[38:39] op_sel_hi:[1,0,1]
	v_pk_fma_f32 v[40:41], v[14:15], v[88:89], v[40:41] op_sel:[0,1,0] op_sel_hi:[1,1,1]
	v_pk_fma_f32 v[38:39], v[16:17], v[90:91], v[38:39] op_sel_hi:[1,0,1]
	v_pk_fma_f32 v[40:41], v[16:17], v[90:91], v[40:41] op_sel:[0,1,0] op_sel_hi:[1,1,1]
	s_waitcnt lgkmcnt(0)
	v_pk_fma_f32 v[38:39], v[18:19], v[92:93], v[38:39] op_sel_hi:[1,0,1]
	v_pk_fma_f32 v[40:41], v[18:19], v[92:93], v[40:41] op_sel:[0,1,0] op_sel_hi:[1,1,1]
	v_pk_fma_f32 v[38:39], v[20:21], v[94:95], v[38:39] op_sel_hi:[1,0,1]
	v_pk_fma_f32 v[40:41], v[20:21], v[94:95], v[40:41] op_sel:[0,1,0] op_sel_hi:[1,1,1]
	v_mul_f32_e32 v51, v100, v50
	v_add_f32_dpp v38, v38, v38 row_ror:8 row_mask:0xf bank_mask:0x3 bound_ctrl:1
	v_add_f32_dpp v39, v39, v39 row_ror:8 row_mask:0xf bank_mask:0x3 bound_ctrl:1
	v_add_f32_dpp v38, v40, v40 row_ror:8 row_mask:0xf bank_mask:0xc bound_ctrl:1
	v_add_f32_dpp v39, v41, v41 row_ror:8 row_mask:0xf bank_mask:0xc bound_ctrl:1
	ds_read_b128 v[56:59], v2 offset:22784
	v_add_f32_dpp v38, v38, v38 row_half_mirror row_mask:0xf bank_mask:0x5 bound_ctrl:1
	v_add_f32_dpp v38, v39, v39 row_half_mirror row_mask:0xf bank_mask:0xa bound_ctrl:1
	ds_read_b128 v[60:63], v2 offset:23040
	ds_read_b128 v[64:67], v2 offset:23296
	v_add_f32_dpp v38, v38, v38 quad_perm:[1,0,3,2] row_mask:0xf bank_mask:0xf bound_ctrl:1
	ds_read_b128 v[68:71], v2 offset:23552
	ds_read_b64 v[72:73], v3 offset:30464
	v_add_f32_dpp v38, v38, v38 quad_perm:[2,3,0,1] row_mask:0xf bank_mask:0xf bound_ctrl:1
	ds_read_b128 v[76:79], v1 offset:31072
	v_cmp_gt_f32_e32 vcc, 0x2b8cbccc, v51
	v_fmac_f32_dpp v96, -v38, v51 row_newbcast:0 row_mask:0xf bank_mask:0xf bound_ctrl:1
	v_fmac_f32_dpp v97, -v38, v51 row_newbcast:4 row_mask:0xf bank_mask:0xf bound_ctrl:1
	v_pk_mul_f32 v[44:45], v[96:97], v[100:101] op_sel:[0,1] op_sel_hi:[1,1]
	v_pk_mul_f32 v[48:49], v[44:45], v[102:103] op_sel_hi:[1,0]
	v_rcp_f32_e32 v52, v51
	s_add_u32 s14, s14, 0x1000
	s_addc_u32 s15, s15, 0
	v_fmac_f32_dpp v48, v38, v51 row_newbcast:8 row_mask:0xf bank_mask:0xf bound_ctrl:1
	v_fmac_f32_dpp v49, v38, v51 row_newbcast:12 row_mask:0xf bank_mask:0xf bound_ctrl:1
	s_cbranch_vccnz .Lgd2_rare1_5
.Lgd2_back1_5:
	v_cvt_pk_bf16_f32 v54, v48, v49
	v_pk_mul_f32 v[46:47], v[44:45], v[52:53] op_sel_hi:[1,0]
	v_pk_fma_f32 v[6:7], v[80:81], v[46:47], v[6:7] op_sel_hi:[0,1,1]
	v_pk_fma_f32 v[8:9], v[82:83], v[46:47], v[8:9] op_sel_hi:[0,1,1]
	v_pk_fma_f32 v[10:11], v[84:85], v[46:47], v[10:11] op_sel_hi:[0,1,1]
	v_pk_fma_f32 v[12:13], v[86:87], v[46:47], v[12:13] op_sel_hi:[0,1,1]
	v_pk_fma_f32 v[14:15], v[88:89], v[46:47], v[14:15] op_sel_hi:[0,1,1]
	v_pk_fma_f32 v[16:17], v[90:91], v[46:47], v[16:17] op_sel_hi:[0,1,1]
	v_pk_fma_f32 v[18:19], v[92:93], v[46:47], v[18:19] op_sel_hi:[0,1,1]
	v_pk_fma_f32 v[20:21], v[94:95], v[46:47], v[20:21] op_sel_hi:[0,1,1]
	global_store_dword v154, v54, s[14:15] offset:-4096
	s_waitcnt lgkmcnt(5)
	v_pk_mul_f32 v[38:39], v[6:7], v[56:57] op_sel_hi:[1,0]
	v_pk_mul_f32 v[40:41], v[6:7], v[56:57] op_sel:[0,1] op_sel_hi:[1,1]
	v_pk_fma_f32 v[38:39], v[8:9], v[58:59], v[38:39] op_sel_hi:[1,0,1]
	v_pk_fma_f32 v[40:41], v[8:9], v[58:59], v[40:41] op_sel:[0,1,0] op_sel_hi:[1,1,1]
	s_waitcnt lgkmcnt(3)
	v_pk_fma_f32 v[38:39], v[10:11], v[60:61], v[38:39] op_sel_hi:[1,0,1]
	v_pk_fma_f32 v[40:41], v[10:11], v[60:61], v[40:41] op_sel:[0,1,0] op_sel_hi:[1,1,1]
	v_pk_fma_f32 v[38:39], v[12:13], v[62:63], v[38:39] op_sel_hi:[1,0,1]
	v_pk_fma_f32 v[40:41], v[12:13], v[62:63], v[40:41] op_sel:[0,1,0] op_sel_hi:[1,1,1]
	v_pk_fma_f32 v[38:39], v[14:15], v[64:65], v[38:39] op_sel_hi:[1,0,1]
	v_pk_fma_f32 v[40:41], v[14:15], v[64:65], v[40:41] op_sel:[0,1,0] op_sel_hi:[1,1,1]
	v_pk_fma_f32 v[38:39], v[16:17], v[66:67], v[38:39] op_sel_hi:[1,0,1]
	v_pk_fma_f32 v[40:41], v[16:17], v[66:67], v[40:41] op_sel:[0,1,0] op_sel_hi:[1,1,1]
	s_waitcnt lgkmcnt(0)
	v_pk_fma_f32 v[38:39], v[18:19], v[68:69], v[38:39] op_sel_hi:[1,0,1]
	v_pk_fma_f32 v[40:41], v[18:19], v[68:69], v[40:41] op_sel:[0,1,0] op_sel_hi:[1,1,1]
	v_pk_fma_f32 v[38:39], v[20:21], v[70:71], v[38:39] op_sel_hi:[1,0,1]
	v_pk_fma_f32 v[40:41], v[20:21], v[70:71], v[40:41] op_sel:[0,1,0] op_sel_hi:[1,1,1]
	v_mul_f32_e32 v50, v76, v51
	v_add_f32_dpp v38, v38, v38 row_ror:8 row_mask:0xf bank_mask:0x3 bound_ctrl:1
	v_add_f32_dpp v39, v39, v39 row_ror:8 row_mask:0xf bank_mask:0x3 bound_ctrl:1
	v_add_f32_dpp v38, v40, v40 row_ror:8 row_mask:0xf bank_mask:0xc bound_ctrl:1
	v_add_f32_dpp v39, v41, v41 row_ror:8 row_mask:0xf bank_mask:0xc bound_ctrl:1
	ds_read_b128 v[80:83], v2 offset:23808
	v_add_f32_dpp v38, v38, v38 row_half_mirror row_mask:0xf bank_mask:0x5 bound_ctrl:1
	v_add_f32_dpp v38, v39, v39 row_half_mirror row_mask:0xf bank_mask:0xa bound_ctrl:1
	ds_read_b128 v[84:87], v2 offset:24064
	ds_read_b128 v[88:91], v2 offset:24320
	v_add_f32_dpp v38, v38, v38 quad_perm:[1,0,3,2] row_mask:0xf bank_mask:0xf bound_ctrl:1
	ds_read_b128 v[92:95], v2 offset:24576
	ds_read_b64 v[96:97], v3 offset:30720
	v_add_f32_dpp v38, v38, v38 quad_perm:[2,3,0,1] row_mask:0xf bank_mask:0xf bound_ctrl:1
	ds_read_b128 v[100:103], v1 offset:31088
	v_cmp_gt_f32_e32 vcc, 0x2b8cbccc, v50
	v_fmac_f32_dpp v72, -v38, v50 row_newbcast:0 row_mask:0xf bank_mask:0xf bound_ctrl:1
	v_fmac_f32_dpp v73, -v38, v50 row_newbcast:4 row_mask:0xf bank_mask:0xf bound_ctrl:1
	v_pk_mul_f32 v[44:45], v[72:73], v[76:77] op_sel:[0,1] op_sel_hi:[1,1]
	v_pk_mul_f32 v[48:49], v[44:45], v[78:79] op_sel_hi:[1,0]
	v_rcp_f32_e32 v52, v50
	s_add_u32 s14, s14, 0x1000
	s_addc_u32 s15, s15, 0
	v_fmac_f32_dpp v48, v38, v50 row_newbcast:8 row_mask:0xf bank_mask:0xf bound_ctrl:1
	v_fmac_f32_dpp v49, v38, v50 row_newbcast:12 row_mask:0xf bank_mask:0xf bound_ctrl:1
	s_cbranch_vccnz .Lgd2_rare1_6
.Lgd2_back1_6:
	v_cvt_pk_bf16_f32 v54, v48, v49
	v_pk_mul_f32 v[46:47], v[44:45], v[52:53] op_sel_hi:[1,0]
	v_pk_fma_f32 v[6:7], v[56:57], v[46:47], v[6:7] op_sel_hi:[0,1,1]
	v_pk_fma_f32 v[8:9], v[58:59], v[46:47], v[8:9] op_sel_hi:[0,1,1]
	v_pk_fma_f32 v[10:11], v[60:61], v[46:47], v[10:11] op_sel_hi:[0,1,1]
	v_pk_fma_f32 v[12:13], v[62:63], v[46:47], v[12:13] op_sel_hi:[0,1,1]
	v_pk_fma_f32 v[14:15], v[64:65], v[46:47], v[14:15] op_sel_hi:[0,1,1]
	v_pk_fma_f32 v[16:17], v[66:67], v[46:47], v[16:17] op_sel_hi:[0,1,1]
	v_pk_fma_f32 v[18:19], v[68:69], v[46:47], v[18:19] op_sel_hi:[0,1,1]
	v_pk_fma_f32 v[20:21], v[70:71], v[46:47], v[20:21] op_sel_hi:[0,1,1]
	global_store_dword v154, v54, s[14:15] offset:-4096
	s_waitcnt lgkmcnt(5)
	v_pk_mul_f32 v[38:39], v[6:7], v[80:81] op_sel_hi:[1,0]
	v_pk_mul_f32 v[40:41], v[6:7], v[80:81] op_sel:[0,1] op_sel_hi:[1,1]
	v_pk_fma_f32 v[38:39], v[8:9], v[82:83], v[38:39] op_sel_hi:[1,0,1]
	v_pk_fma_f32 v[40:41], v[8:9], v[82:83], v[40:41] op_sel:[0,1,0] op_sel_hi:[1,1,1]
	s_waitcnt lgkmcnt(3)
	v_pk_fma_f32 v[38:39], v[10:11], v[84:85], v[38:39] op_sel_hi:[1,0,1]
	v_pk_fma_f32 v[40:41], v[10:11], v[84:85], v[40:41] op_sel:[0,1,0] op_sel_hi:[1,1,1]
	v_pk_fma_f32 v[38:39], v[12:13], v[86:87], v[38:39] op_sel_hi:[1,0,1]
	v_pk_fma_f32 v[40:41], v[12:13], v[86:87], v[40:41] op_sel:[0,1,0] op_sel_hi:[1,1,1]
	v_pk_fma_f32 v[38:39], v[14:15], v[88:89], v[38:39] op_sel_hi:[1,0,1]
	v_pk_fma_f32 v[40:41], v[14:15], v[88:89], v[40:41] op_sel:[0,1,0] op_sel_hi:[1,1,1]
	v_pk_fma_f32 v[38:39], v[16:17], v[90:91], v[38:39] op_sel_hi:[1,0,1]
	v_pk_fma_f32 v[40:41], v[16:17], v[90:91], v[40:41] op_sel:[0,1,0] op_sel_hi:[1,1,1]
	s_waitcnt lgkmcnt(0)
	v_pk_fma_f32 v[38:39], v[18:19], v[92:93], v[38:39] op_sel_hi:[1,0,1]
	v_pk_fma_f32 v[40:41], v[18:19], v[92:93], v[40:41] op_sel:[0,1,0] op_sel_hi:[1,1,1]
	v_pk_fma_f32 v[38:39], v[20:21], v[94:95], v[38:39] op_sel_hi:[1,0,1]
	v_pk_fma_f32 v[40:41], v[20:21], v[94:95], v[40:41] op_sel:[0,1,0] op_sel_hi:[1,1,1]
	v_mul_f32_e32 v51, v100, v50
	v_add_f32_dpp v38, v38, v38 row_ror:8 row_mask:0xf bank_mask:0x3 bound_ctrl:1
	v_add_f32_dpp v39, v39, v39 row_ror:8 row_mask:0xf bank_mask:0x3 bound_ctrl:1
	v_add_f32_dpp v38, v40, v40 row_ror:8 row_mask:0xf bank_mask:0xc bound_ctrl:1
	v_add_f32_dpp v39, v41, v41 row_ror:8 row_mask:0xf bank_mask:0xc bound_ctrl:1
	ds_read_b128 v[56:59], v2 offset:33024
	v_add_f32_dpp v38, v38, v38 row_half_mirror row_mask:0xf bank_mask:0x5 bound_ctrl:1
	v_add_f32_dpp v38, v39, v39 row_half_mirror row_mask:0xf bank_mask:0xa bound_ctrl:1
	ds_read_b128 v[60:63], v2 offset:33280
	ds_read_b128 v[64:67], v2 offset:33536
	v_add_f32_dpp v38, v38, v38 quad_perm:[1,0,3,2] row_mask:0xf bank_mask:0xf bound_ctrl:1
	ds_read_b128 v[68:71], v2 offset:33792
	ds_read_b64 v[72:73], v3 offset:45312
	v_add_f32_dpp v38, v38, v38 quad_perm:[2,3,0,1] row_mask:0xf bank_mask:0xf bound_ctrl:1
	ds_read_b128 v[76:79], v1 offset:47360
	v_cmp_gt_f32_e32 vcc, 0x2b8cbccc, v51
	v_fmac_f32_dpp v96, -v38, v51 row_newbcast:0 row_mask:0xf bank_mask:0xf bound_ctrl:1
	v_fmac_f32_dpp v97, -v38, v51 row_newbcast:4 row_mask:0xf bank_mask:0xf bound_ctrl:1
	v_pk_mul_f32 v[44:45], v[96:97], v[100:101] op_sel:[0,1] op_sel_hi:[1,1]
	v_pk_mul_f32 v[48:49], v[44:45], v[102:103] op_sel_hi:[1,0]
	v_rcp_f32_e32 v52, v51
	s_add_u32 s14, s14, 0x1000
	s_addc_u32 s15, s15, 0
	v_fmac_f32_dpp v48, v38, v51 row_newbcast:8 row_mask:0xf bank_mask:0xf bound_ctrl:1
	v_fmac_f32_dpp v49, v38, v51 row_newbcast:12 row_mask:0xf bank_mask:0xf bound_ctrl:1
	s_cbranch_vccnz .Lgd2_rare1_7
.Lgd2_back1_7:
	v_cvt_pk_bf16_f32 v54, v48, v49
	v_pk_mul_f32 v[46:47], v[44:45], v[52:53] op_sel_hi:[1,0]
	v_pk_fma_f32 v[6:7], v[80:81], v[46:47], v[6:7] op_sel_hi:[0,1,1]
	v_pk_fma_f32 v[8:9], v[82:83], v[46:47], v[8:9] op_sel_hi:[0,1,1]
	v_pk_fma_f32 v[10:11], v[84:85], v[46:47], v[10:11] op_sel_hi:[0,1,1]
	v_pk_fma_f32 v[12:13], v[86:87], v[46:47], v[12:13] op_sel_hi:[0,1,1]
	v_pk_fma_f32 v[14:15], v[88:89], v[46:47], v[14:15] op_sel_hi:[0,1,1]
	v_pk_fma_f32 v[16:17], v[90:91], v[46:47], v[16:17] op_sel_hi:[0,1,1]
	v_pk_fma_f32 v[18:19], v[92:93], v[46:47], v[18:19] op_sel_hi:[0,1,1]
	v_pk_fma_f32 v[20:21], v[94:95], v[46:47], v[20:21] op_sel_hi:[0,1,1]
	global_store_dword v154, v54, s[14:15] offset:-4096
	s_waitcnt vmcnt(8)
	v_lshlrev_b32_e32 v116, 16, v108
	v_lshlrev_b32_e32 v117, 16, v109
	v_and_b32_e32 v118, s17, v108
	v_and_b32_e32 v119, s17, v109
	v_lshlrev_b32_e32 v120, 16, v110
	v_and_b32_e32 v121, s17, v110
	v_lshlrev_b32_e32 v122, 16, v111
	v_and_b32_e32 v123, s17, v111
	v_lshlrev_b32_e32 v124, 16, v112
	v_and_b32_e32 v125, s17, v112
	ds_write_b128 v32, v[116:119] offset:256
	ds_write_b64 v33, v[120:121] offset:256
	ds_write_b64 v34, v[122:123] offset:256
	ds_write_b64 v34, v[124:125] offset:384
	ds_write_b32 v35, v113 offset:256
	s_add_i32 s16, s16, 8
	s_waitcnt lgkmcnt(0)
	s_barrier
	s_cmpk_lt_u32 s16, 0x800
	s_cbranch_scc0 .Lgd2_done
	global_load_dword v108, v36, s[8:9]
	global_load_dword v109, v36, s[8:9] offset:-2048
	global_load_dword v111, v104, s[8:9] offset:2048
	global_load_dword v110, v37, s[10:11]
	global_load_dword v112, v105, s[10:11]
	global_load_dword v113, v106, s[12:13]
	s_add_u32 s8, s8, 0xc000
	s_addc_u32 s9, s9, 0
	s_add_u32 s10, s10, 0x20000
	s_addc_u32 s11, s11, 0
	s_add_u32 s12, s12, 0x400
	s_addc_u32 s13, s13, 0
	s_waitcnt lgkmcnt(5)
	v_pk_mul_f32 v[38:39], v[6:7], v[56:57] op_sel_hi:[1,0]
	v_pk_mul_f32 v[40:41], v[6:7], v[56:57] op_sel:[0,1] op_sel_hi:[1,1]
	v_pk_fma_f32 v[38:39], v[8:9], v[58:59], v[38:39] op_sel_hi:[1,0,1]
	v_pk_fma_f32 v[40:41], v[8:9], v[58:59], v[40:41] op_sel:[0,1,0] op_sel_hi:[1,1,1]
	s_waitcnt lgkmcnt(3)
	v_pk_fma_f32 v[38:39], v[10:11], v[60:61], v[38:39] op_sel_hi:[1,0,1]
	v_pk_fma_f32 v[40:41], v[10:11], v[60:61], v[40:41] op_sel:[0,1,0] op_sel_hi:[1,1,1]
	v_pk_fma_f32 v[38:39], v[12:13], v[62:63], v[38:39] op_sel_hi:[1,0,1]
	v_pk_fma_f32 v[40:41], v[12:13], v[62:63], v[40:41] op_sel:[0,1,0] op_sel_hi:[1,1,1]
	v_pk_fma_f32 v[38:39], v[14:15], v[64:65], v[38:39] op_sel_hi:[1,0,1]
	v_pk_fma_f32 v[40:41], v[14:15], v[64:65], v[40:41] op_sel:[0,1,0] op_sel_hi:[1,1,1]
	v_pk_fma_f32 v[38:39], v[16:17], v[66:67], v[38:39] op_sel_hi:[1,0,1]
	v_pk_fma_f32 v[40:41], v[16:17], v[66:67], v[40:41] op_sel:[0,1,0] op_sel_hi:[1,1,1]
	s_waitcnt lgkmcnt(0)
	v_pk_fma_f32 v[38:39], v[18:19], v[68:69], v[38:39] op_sel_hi:[1,0,1]
	v_pk_fma_f32 v[40:41], v[18:19], v[68:69], v[40:41] op_sel:[0,1,0] op_sel_hi:[1,1,1]
	v_pk_fma_f32 v[38:39], v[20:21], v[70:71], v[38:39] op_sel_hi:[1,0,1]
	v_pk_fma_f32 v[40:41], v[20:21], v[70:71], v[40:41] op_sel:[0,1,0] op_sel_hi:[1,1,1]
	v_mul_f32_e32 v50, v76, v51
	v_add_f32_dpp v38, v38, v38 row_ror:8 row_mask:0xf bank_mask:0x3 bound_ctrl:1
	v_add_f32_dpp v39, v39, v39 row_ror:8 row_mask:0xf bank_mask:0x3 bound_ctrl:1
	v_add_f32_dpp v38, v40, v40 row_ror:8 row_mask:0xf bank_mask:0xc bound_ctrl:1
	v_add_f32_dpp v39, v41, v41 row_ror:8 row_mask:0xf bank_mask:0xc bound_ctrl:1
	ds_read_b128 v[80:83], v2 offset:34048
	v_add_f32_dpp v38, v38, v38 row_half_mirror row_mask:0xf bank_mask:0x5 bound_ctrl:1
	v_add_f32_dpp v38, v39, v39 row_half_mirror row_mask:0xf bank_mask:0xa bound_ctrl:1
	ds_read_b128 v[84:87], v2 offset:34304
	ds_read_b128 v[88:91], v2 offset:34560
	v_add_f32_dpp v38, v38, v38 quad_perm:[1,0,3,2] row_mask:0xf bank_mask:0xf bound_ctrl:1
	ds_read_b128 v[92:95], v2 offset:34816
	ds_read_b64 v[96:97], v3 offset:45568
	v_add_f32_dpp v38, v38, v38 quad_perm:[2,3,0,1] row_mask:0xf bank_mask:0xf bound_ctrl:1
	ds_read_b128 v[100:103], v1 offset:47376
	v_cmp_gt_f32_e32 vcc, 0x2b8cbccc, v50
	v_fmac_f32_dpp v72, -v38, v50 row_newbcast:0 row_mask:0xf bank_mask:0xf bound_ctrl:1
	v_fmac_f32_dpp v73, -v38, v50 row_newbcast:4 row_mask:0xf bank_mask:0xf bound_ctrl:1
	v_pk_mul_f32 v[44:45], v[72:73], v[76:77] op_sel:[0,1] op_sel_hi:[1,1]
	v_pk_mul_f32 v[48:49], v[44:45], v[78:79] op_sel_hi:[1,0]
	v_rcp_f32_e32 v52, v50
	s_add_u32 s14, s14, 0x1000
	s_addc_u32 s15, s15, 0
	v_fmac_f32_dpp v48, v38, v50 row_newbcast:8 row_mask:0xf bank_mask:0xf bound_ctrl:1
	v_fmac_f32_dpp v49, v38, v50 row_newbcast:12 row_mask:0xf bank_mask:0xf bound_ctrl:1
	s_cbranch_vccnz .Lgd2_rare2_0
.Lgd2_back2_0:
	v_cvt_pk_bf16_f32 v54, v48, v49
	v_pk_mul_f32 v[46:47], v[44:45], v[52:53] op_sel_hi:[1,0]
	v_pk_fma_f32 v[6:7], v[56:57], v[46:47], v[6:7] op_sel_hi:[0,1,1]
	v_pk_fma_f32 v[8:9], v[58:59], v[46:47], v[8:9] op_sel_hi:[0,1,1]
	v_pk_fma_f32 v[10:11], v[60:61], v[46:47], v[10:11] op_sel_hi:[0,1,1]
	v_pk_fma_f32 v[12:13], v[62:63], v[46:47], v[12:13] op_sel_hi:[0,1,1]
	v_pk_fma_f32 v[14:15], v[64:65], v[46:47], v[14:15] op_sel_hi:[0,1,1]
	v_pk_fma_f32 v[16:17], v[66:67], v[46:47], v[16:17] op_sel_hi:[0,1,1]
	v_pk_fma_f32 v[18:19], v[68:69], v[46:47], v[18:19] op_sel_hi:[0,1,1]
	v_pk_fma_f32 v[20:21], v[70:71], v[46:47], v[20:21] op_sel_hi:[0,1,1]
	global_store_dword v154, v54, s[14:15] offset:-4096
	s_waitcnt lgkmcnt(5)
	v_pk_mul_f32 v[38:39], v[6:7], v[80:81] op_sel_hi:[1,0]
	v_pk_mul_f32 v[40:41], v[6:7], v[80:81] op_sel:[0,1] op_sel_hi:[1,1]
	v_pk_fma_f32 v[38:39], v[8:9], v[82:83], v[38:39] op_sel_hi:[1,0,1]
	v_pk_fma_f32 v[40:41], v[8:9], v[82:83], v[40:41] op_sel:[0,1,0] op_sel_hi:[1,1,1]
	s_waitcnt lgkmcnt(3)
	v_pk_fma_f32 v[38:39], v[10:11], v[84:85], v[38:39] op_sel_hi:[1,0,1]
	v_pk_fma_f32 v[40:41], v[10:11], v[84:85], v[40:41] op_sel:[0,1,0] op_sel_hi:[1,1,1]
	v_pk_fma_f32 v[38:39], v[12:13], v[86:87], v[38:39] op_sel_hi:[1,0,1]
	v_pk_fma_f32 v[40:41], v[12:13], v[86:87], v[40:41] op_sel:[0,1,0] op_sel_hi:[1,1,1]
	v_pk_fma_f32 v[38:39], v[14:15], v[88:89], v[38:39] op_sel_hi:[1,0,1]
	v_pk_fma_f32 v[40:41], v[14:15], v[88:89], v[40:41] op_sel:[0,1,0] op_sel_hi:[1,1,1]
	v_pk_fma_f32 v[38:39], v[16:17], v[90:91], v[38:39] op_sel_hi:[1,0,1]
	v_pk_fma_f32 v[40:41], v[16:17], v[90:91], v[40:41] op_sel:[0,1,0] op_sel_hi:[1,1,1]
	s_waitcnt lgkmcnt(0)
	v_pk_fma_f32 v[38:39], v[18:19], v[92:93], v[38:39] op_sel_hi:[1,0,1]
	v_pk_fma_f32 v[40:41], v[18:19], v[92:93], v[40:41] op_sel:[0,1,0] op_sel_hi:[1,1,1]
	v_pk_fma_f32 v[38:39], v[20:21], v[94:95], v[38:39] op_sel_hi:[1,0,1]
	v_pk_fma_f32 v[40:41], v[20:21], v[94:95], v[40:41] op_sel:[0,1,0] op_sel_hi:[1,1,1]
	v_mul_f32_e32 v51, v100, v50
	v_add_f32_dpp v38, v38, v38 row_ror:8 row_mask:0xf bank_mask:0x3 bound_ctrl:1
	v_add_f32_dpp v39, v39, v39 row_ror:8 row_mask:0xf bank_mask:0x3 bound_ctrl:1
	v_add_f32_dpp v38, v40, v40 row_ror:8 row_mask:0xf bank_mask:0xc bound_ctrl:1
	v_add_f32_dpp v39, v41, v41 row_ror:8 row_mask:0xf bank_mask:0xc bound_ctrl:1
	ds_read_b128 v[56:59], v2 offset:35072
	v_add_f32_dpp v38, v38, v38 row_half_mirror row_mask:0xf bank_mask:0x5 bound_ctrl:1
	v_add_f32_dpp v38, v39, v39 row_half_mirror row_mask:0xf bank_mask:0xa bound_ctrl:1
	ds_read_b128 v[60:63], v2 offset:35328
	ds_read_b128 v[64:67], v2 offset:35584
	v_add_f32_dpp v38, v38, v38 quad_perm:[1,0,3,2] row_mask:0xf bank_mask:0xf bound_ctrl:1
	ds_read_b128 v[68:71], v2 offset:35840
	ds_read_b64 v[72:73], v3 offset:45824
	v_add_f32_dpp v38, v38, v38 quad_perm:[2,3,0,1] row_mask:0xf bank_mask:0xf bound_ctrl:1
	ds_read_b128 v[76:79], v1 offset:47392
	v_cmp_gt_f32_e32 vcc, 0x2b8cbccc, v51
	v_fmac_f32_dpp v96, -v38, v51 row_newbcast:0 row_mask:0xf bank_mask:0xf bound_ctrl:1
	v_fmac_f32_dpp v97, -v38, v51 row_newbcast:4 row_mask:0xf bank_mask:0xf bound_ctrl:1
	v_pk_mul_f32 v[44:45], v[96:97], v[100:101] op_sel:[0,1] op_sel_hi:[1,1]
	v_pk_mul_f32 v[48:49], v[44:45], v[102:103] op_sel_hi:[1,0]
	v_rcp_f32_e32 v52, v51
	s_add_u32 s14, s14, 0x1000
	s_addc_u32 s15, s15, 0
	v_fmac_f32_dpp v48, v38, v51 row_newbcast:8 row_mask:0xf bank_mask:0xf bound_ctrl:1
	v_fmac_f32_dpp v49, v38, v51 row_newbcast:12 row_mask:0xf bank_mask:0xf bound_ctrl:1
	s_cbranch_vccnz .Lgd2_rare2_1
.Lgd2_back2_1:
	v_cvt_pk_bf16_f32 v54, v48, v49
	v_pk_mul_f32 v[46:47], v[44:45], v[52:53] op_sel_hi:[1,0]
	v_pk_fma_f32 v[6:7], v[80:81], v[46:47], v[6:7] op_sel_hi:[0,1,1]
	v_pk_fma_f32 v[8:9], v[82:83], v[46:47], v[8:9] op_sel_hi:[0,1,1]
	v_pk_fma_f32 v[10:11], v[84:85], v[46:47], v[10:11] op_sel_hi:[0,1,1]
	v_pk_fma_f32 v[12:13], v[86:87], v[46:47], v[12:13] op_sel_hi:[0,1,1]
	v_pk_fma_f32 v[14:15], v[88:89], v[46:47], v[14:15] op_sel_hi:[0,1,1]
	v_pk_fma_f32 v[16:17], v[90:91], v[46:47], v[16:17] op_sel_hi:[0,1,1]
	v_pk_fma_f32 v[18:19], v[92:93], v[46:47], v[18:19] op_sel_hi:[0,1,1]
	v_pk_fma_f32 v[20:21], v[94:95], v[46:47], v[20:21] op_sel_hi:[0,1,1]
	global_store_dword v154, v54, s[14:15] offset:-4096
	s_waitcnt lgkmcnt(5)
	v_pk_mul_f32 v[38:39], v[6:7], v[56:57] op_sel_hi:[1,0]
	v_pk_mul_f32 v[40:41], v[6:7], v[56:57] op_sel:[0,1] op_sel_hi:[1,1]
	v_pk_fma_f32 v[38:39], v[8:9], v[58:59], v[38:39] op_sel_hi:[1,0,1]
	v_pk_fma_f32 v[40:41], v[8:9], v[58:59], v[40:41] op_sel:[0,1,0] op_sel_hi:[1,1,1]
	s_waitcnt lgkmcnt(3)
	v_pk_fma_f32 v[38:39], v[10:11], v[60:61], v[38:39] op_sel_hi:[1,0,1]
	v_pk_fma_f32 v[40:41], v[10:11], v[60:61], v[40:41] op_sel:[0,1,0] op_sel_hi:[1,1,1]
	v_pk_fma_f32 v[38:39], v[12:13], v[62:63], v[38:39] op_sel_hi:[1,0,1]
	v_pk_fma_f32 v[40:41], v[12:13], v[62:63], v[40:41] op_sel:[0,1,0] op_sel_hi:[1,1,1]
	v_pk_fma_f32 v[38:39], v[14:15], v[64:65], v[38:39] op_sel_hi:[1,0,1]
	v_pk_fma_f32 v[40:41], v[14:15], v[64:65], v[40:41] op_sel:[0,1,0] op_sel_hi:[1,1,1]
	v_pk_fma_f32 v[38:39], v[16:17], v[66:67], v[38:39] op_sel_hi:[1,0,1]
	v_pk_fma_f32 v[40:41], v[16:17], v[66:67], v[40:41] op_sel:[0,1,0] op_sel_hi:[1,1,1]
	s_waitcnt lgkmcnt(0)
	v_pk_fma_f32 v[38:39], v[18:19], v[68:69], v[38:39] op_sel_hi:[1,0,1]
	v_pk_fma_f32 v[40:41], v[18:19], v[68:69], v[40:41] op_sel:[0,1,0] op_sel_hi:[1,1,1]
	v_pk_fma_f32 v[38:39], v[20:21], v[70:71], v[38:39] op_sel_hi:[1,0,1]
	v_pk_fma_f32 v[40:41], v[20:21], v[70:71], v[40:41] op_sel:[0,1,0] op_sel_hi:[1,1,1]
	v_mul_f32_e32 v50, v76, v51
	v_add_f32_dpp v38, v38, v38 row_ror:8 row_mask:0xf bank_mask:0x3 bound_ctrl:1
	v_add_f32_dpp v39, v39, v39 row_ror:8 row_mask:0xf bank_mask:0x3 bound_ctrl:1
	v_add_f32_dpp v38, v40, v40 row_ror:8 row_mask:0xf bank_mask:0xc bound_ctrl:1
	v_add_f32_dpp v39, v41, v41 row_ror:8 row_mask:0xf bank_mask:0xc bound_ctrl:1
	ds_read_b128 v[80:83], v2 offset:36096
	v_add_f32_dpp v38, v38, v38 row_half_mirror row_mask:0xf bank_mask:0x5 bound_ctrl:1
	v_add_f32_dpp v38, v39, v39 row_half_mirror row_mask:0xf bank_mask:0xa bound_ctrl:1
	ds_read_b128 v[84:87], v2 offset:36352
	ds_read_b128 v[88:91], v2 offset:36608
	v_add_f32_dpp v38, v38, v38 quad_perm:[1,0,3,2] row_mask:0xf bank_mask:0xf bound_ctrl:1
	ds_read_b128 v[92:95], v2 offset:36864
	ds_read_b64 v[96:97], v3 offset:46080
	v_add_f32_dpp v38, v38, v38 quad_perm:[2,3,0,1] row_mask:0xf bank_mask:0xf bound_ctrl:1
	ds_read_b128 v[100:103], v1 offset:47408
	v_cmp_gt_f32_e32 vcc, 0x2b8cbccc, v50
	v_fmac_f32_dpp v72, -v38, v50 row_newbcast:0 row_mask:0xf bank_mask:0xf bound_ctrl:1
	v_fmac_f32_dpp v73, -v38, v50 row_newbcast:4 row_mask:0xf bank_mask:0xf bound_ctrl:1
	v_pk_mul_f32 v[44:45], v[72:73], v[76:77] op_sel:[0,1] op_sel_hi:[1,1]
	v_pk_mul_f32 v[48:49], v[44:45], v[78:79] op_sel_hi:[1,0]
	v_rcp_f32_e32 v52, v50
	s_add_u32 s14, s14, 0x1000
	s_addc_u32 s15, s15, 0
	v_fmac_f32_dpp v48, v38, v50 row_newbcast:8 row_mask:0xf bank_mask:0xf bound_ctrl:1
	v_fmac_f32_dpp v49, v38, v50 row_newbcast:12 row_mask:0xf bank_mask:0xf bound_ctrl:1
	s_cbranch_vccnz .Lgd2_rare2_2
.Lgd2_back2_2:
	v_cvt_pk_bf16_f32 v54, v48, v49
	v_pk_mul_f32 v[46:47], v[44:45], v[52:53] op_sel_hi:[1,0]
	v_pk_fma_f32 v[6:7], v[56:57], v[46:47], v[6:7] op_sel_hi:[0,1,1]
	v_pk_fma_f32 v[8:9], v[58:59], v[46:47], v[8:9] op_sel_hi:[0,1,1]
	v_pk_fma_f32 v[10:11], v[60:61], v[46:47], v[10:11] op_sel_hi:[0,1,1]
	v_pk_fma_f32 v[12:13], v[62:63], v[46:47], v[12:13] op_sel_hi:[0,1,1]
	v_pk_fma_f32 v[14:15], v[64:65], v[46:47], v[14:15] op_sel_hi:[0,1,1]
	v_pk_fma_f32 v[16:17], v[66:67], v[46:47], v[16:17] op_sel_hi:[0,1,1]
	v_pk_fma_f32 v[18:19], v[68:69], v[46:47], v[18:19] op_sel_hi:[0,1,1]
	v_pk_fma_f32 v[20:21], v[70:71], v[46:47], v[20:21] op_sel_hi:[0,1,1]
	global_store_dword v154, v54, s[14:15] offset:-4096
	s_waitcnt lgkmcnt(5)
	v_pk_mul_f32 v[38:39], v[6:7], v[80:81] op_sel_hi:[1,0]
	v_pk_mul_f32 v[40:41], v[6:7], v[80:81] op_sel:[0,1] op_sel_hi:[1,1]
	v_pk_fma_f32 v[38:39], v[8:9], v[82:83], v[38:39] op_sel_hi:[1,0,1]
	v_pk_fma_f32 v[40:41], v[8:9], v[82:83], v[40:41] op_sel:[0,1,0] op_sel_hi:[1,1,1]
	s_waitcnt lgkmcnt(3)
	v_pk_fma_f32 v[38:39], v[10:11], v[84:85], v[38:39] op_sel_hi:[1,0,1]
	v_pk_fma_f32 v[40:41], v[10:11], v[84:85], v[40:41] op_sel:[0,1,0] op_sel_hi:[1,1,1]
	v_pk_fma_f32 v[38:39], v[12:13], v[86:87], v[38:39] op_sel_hi:[1,0,1]
	v_pk_fma_f32 v[40:41], v[12:13], v[86:87], v[40:41] op_sel:[0,1,0] op_sel_hi:[1,1,1]
	v_pk_fma_f32 v[38:39], v[14:15], v[88:89], v[38:39] op_sel_hi:[1,0,1]
	v_pk_fma_f32 v[40:41], v[14:15], v[88:89], v[40:41] op_sel:[0,1,0] op_sel_hi:[1,1,1]
	v_pk_fma_f32 v[38:39], v[16:17], v[90:91], v[38:39] op_sel_hi:[1,0,1]
	v_pk_fma_f32 v[40:41], v[16:17], v[90:91], v[40:41] op_sel:[0,1,0] op_sel_hi:[1,1,1]
	s_waitcnt lgkmcnt(0)
	v_pk_fma_f32 v[38:39], v[18:19], v[92:93], v[38:39] op_sel_hi:[1,0,1]
	v_pk_fma_f32 v[40:41], v[18:19], v[92:93], v[40:41] op_sel:[0,1,0] op_sel_hi:[1,1,1]
	v_pk_fma_f32 v[38:39], v[20:21], v[94:95], v[38:39] op_sel_hi:[1,0,1]
	v_pk_fma_f32 v[40:41], v[20:21], v[94:95], v[40:41] op_sel:[0,1,0] op_sel_hi:[1,1,1]
	v_mul_f32_e32 v51, v100, v50
	v_add_f32_dpp v38, v38, v38 row_ror:8 row_mask:0xf bank_mask:0x3 bound_ctrl:1
	v_add_f32_dpp v39, v39, v39 row_ror:8 row_mask:0xf bank_mask:0x3 bound_ctrl:1
	v_add_f32_dpp v38, v40, v40 row_ror:8 row_mask:0xf bank_mask:0xc bound_ctrl:1
	v_add_f32_dpp v39, v41, v41 row_ror:8 row_mask:0xf bank_mask:0xc bound_ctrl:1
	ds_read_b128 v[56:59], v2 offset:37120
	v_add_f32_dpp v38, v38, v38 row_half_mirror row_mask:0xf bank_mask:0x5 bound_ctrl:1
	v_add_f32_dpp v38, v39, v39 row_half_mirror row_mask:0xf bank_mask:0xa bound_ctrl:1
	ds_read_b128 v[60:63], v2 offset:37376
	ds_read_b128 v[64:67], v2 offset:37632
	v_add_f32_dpp v38, v38, v38 quad_perm:[1,0,3,2] row_mask:0xf bank_mask:0xf bound_ctrl:1
	ds_read_b128 v[68:71], v2 offset:37888
	ds_read_b64 v[72:73], v3 offset:46336
	v_add_f32_dpp v38, v38, v38 quad_perm:[2,3,0,1] row_mask:0xf bank_mask:0xf bound_ctrl:1
	ds_read_b128 v[76:79], v1 offset:47424
	v_cmp_gt_f32_e32 vcc, 0x2b8cbccc, v51
	v_fmac_f32_dpp v96, -v38, v51 row_newbcast:0 row_mask:0xf bank_mask:0xf bound_ctrl:1
	v_fmac_f32_dpp v97, -v38, v51 row_newbcast:4 row_mask:0xf bank_mask:0xf bound_ctrl:1
	v_pk_mul_f32 v[44:45], v[96:97], v[100:101] op_sel:[0,1] op_sel_hi:[1,1]
	v_pk_mul_f32 v[48:49], v[44:45], v[102:103] op_sel_hi:[1,0]
	v_rcp_f32_e32 v52, v51
	s_add_u32 s14, s14, 0x1000
	s_addc_u32 s15, s15, 0
	v_fmac_f32_dpp v48, v38, v51 row_newbcast:8 row_mask:0xf bank_mask:0xf bound_ctrl:1
	v_fmac_f32_dpp v49, v38, v51 row_newbcast:12 row_mask:0xf bank_mask:0xf bound_ctrl:1
	s_cbranch_vccnz .Lgd2_rare2_3
.Lgd2_back2_3:
	v_cvt_pk_bf16_f32 v54, v48, v49
	v_pk_mul_f32 v[46:47], v[44:45], v[52:53] op_sel_hi:[1,0]
	v_pk_fma_f32 v[6:7], v[80:81], v[46:47], v[6:7] op_sel_hi:[0,1,1]
	v_pk_fma_f32 v[8:9], v[82:83], v[46:47], v[8:9] op_sel_hi:[0,1,1]
	v_pk_fma_f32 v[10:11], v[84:85], v[46:47], v[10:11] op_sel_hi:[0,1,1]
	v_pk_fma_f32 v[12:13], v[86:87], v[46:47], v[12:13] op_sel_hi:[0,1,1]
	v_pk_fma_f32 v[14:15], v[88:89], v[46:47], v[14:15] op_sel_hi:[0,1,1]
	v_pk_fma_f32 v[16:17], v[90:91], v[46:47], v[16:17] op_sel_hi:[0,1,1]
	v_pk_fma_f32 v[18:19], v[92:93], v[46:47], v[18:19] op_sel_hi:[0,1,1]
	v_pk_fma_f32 v[20:21], v[94:95], v[46:47], v[20:21] op_sel_hi:[0,1,1]
	global_store_dword v154, v54, s[14:15] offset:-4096
	s_waitcnt lgkmcnt(5)
	v_pk_mul_f32 v[38:39], v[6:7], v[56:57] op_sel_hi:[1,0]
	v_pk_mul_f32 v[40:41], v[6:7], v[56:57] op_sel:[0,1] op_sel_hi:[1,1]
	v_pk_fma_f32 v[38:39], v[8:9], v[58:59], v[38:39] op_sel_hi:[1,0,1]
	v_pk_fma_f32 v[40:41], v[8:9], v[58:59], v[40:41] op_sel:[0,1,0] op_sel_hi:[1,1,1]
	s_waitcnt lgkmcnt(3)
	v_pk_fma_f32 v[38:39], v[10:11], v[60:61], v[38:39] op_sel_hi:[1,0,1]
	v_pk_fma_f32 v[40:41], v[10:11], v[60:61], v[40:41] op_sel:[0,1,0] op_sel_hi:[1,1,1]
	v_pk_fma_f32 v[38:39], v[12:13], v[62:63], v[38:39] op_sel_hi:[1,0,1]
	v_pk_fma_f32 v[40:41], v[12:13], v[62:63], v[40:41] op_sel:[0,1,0] op_sel_hi:[1,1,1]
	v_pk_fma_f32 v[38:39], v[14:15], v[64:65], v[38:39] op_sel_hi:[1,0,1]
	v_pk_fma_f32 v[40:41], v[14:15], v[64:65], v[40:41] op_sel:[0,1,0] op_sel_hi:[1,1,1]
	v_pk_fma_f32 v[38:39], v[16:17], v[66:67], v[38:39] op_sel_hi:[1,0,1]
	v_pk_fma_f32 v[40:41], v[16:17], v[66:67], v[40:41] op_sel:[0,1,0] op_sel_hi:[1,1,1]
	s_waitcnt lgkmcnt(0)
	v_pk_fma_f32 v[38:39], v[18:19], v[68:69], v[38:39] op_sel_hi:[1,0,1]
	v_pk_fma_f32 v[40:41], v[18:19], v[68:69], v[40:41] op_sel:[0,1,0] op_sel_hi:[1,1,1]
	v_pk_fma_f32 v[38:39], v[20:21], v[70:71], v[38:39] op_sel_hi:[1,0,1]
	v_pk_fma_f32 v[40:41], v[20:21], v[70:71], v[40:41] op_sel:[0,1,0] op_sel_hi:[1,1,1]
	v_mul_f32_e32 v50, v76, v51
	v_add_f32_dpp v38, v38, v38 row_ror:8 row_mask:0xf bank_mask:0x3 bound_ctrl:1
	v_add_f32_dpp v39, v39, v39 row_ror:8 row_mask:0xf bank_mask:0x3 bound_ctrl:1
	v_add_f32_dpp v38, v40, v40 row_ror:8 row_mask:0xf bank_mask:0xc bound_ctrl:1
	v_add_f32_dpp v39, v41, v41 row_ror:8 row_mask:0xf bank_mask:0xc bound_ctrl:1
	ds_read_b128 v[80:83], v2 offset:38144
	v_add_f32_dpp v38, v38, v38 row_half_mirror row_mask:0xf bank_mask:0x5 bound_ctrl:1
	v_add_f32_dpp v38, v39, v39 row_half_mirror row_mask:0xf bank_mask:0xa bound_ctrl:1
	ds_read_b128 v[84:87], v2 offset:38400
	ds_read_b128 v[88:91], v2 offset:38656
	v_add_f32_dpp v38, v38, v38 quad_perm:[1,0,3,2] row_mask:0xf bank_mask:0xf bound_ctrl:1
	ds_read_b128 v[92:95], v2 offset:38912
	ds_read_b64 v[96:97], v3 offset:46592
	v_add_f32_dpp v38, v38, v38 quad_perm:[2,3,0,1] row_mask:0xf bank_mask:0xf bound_ctrl:1
	ds_read_b128 v[100:103], v1 offset:47440
	v_cmp_gt_f32_e32 vcc, 0x2b8cbccc, v50
	v_fmac_f32_dpp v72, -v38, v50 row_newbcast:0 row_mask:0xf bank_mask:0xf bound_ctrl:1
	v_fmac_f32_dpp v73, -v38, v50 row_newbcast:4 row_mask:0xf bank_mask:0xf bound_ctrl:1
	v_pk_mul_f32 v[44:45], v[72:73], v[76:77] op_sel:[0,1] op_sel_hi:[1,1]
	v_pk_mul_f32 v[48:49], v[44:45], v[78:79] op_sel_hi:[1,0]
	v_rcp_f32_e32 v52, v50
	s_add_u32 s14, s14, 0x1000
	s_addc_u32 s15, s15, 0
	v_fmac_f32_dpp v48, v38, v50 row_newbcast:8 row_mask:0xf bank_mask:0xf bound_ctrl:1
	v_fmac_f32_dpp v49, v38, v50 row_newbcast:12 row_mask:0xf bank_mask:0xf bound_ctrl:1
	s_cbranch_vccnz .Lgd2_rare2_4
.Lgd2_back2_4:
	v_cvt_pk_bf16_f32 v54, v48, v49
	v_pk_mul_f32 v[46:47], v[44:45], v[52:53] op_sel_hi:[1,0]
	v_pk_fma_f32 v[6:7], v[56:57], v[46:47], v[6:7] op_sel_hi:[0,1,1]
	v_pk_fma_f32 v[8:9], v[58:59], v[46:47], v[8:9] op_sel_hi:[0,1,1]
	v_pk_fma_f32 v[10:11], v[60:61], v[46:47], v[10:11] op_sel_hi:[0,1,1]
	v_pk_fma_f32 v[12:13], v[62:63], v[46:47], v[12:13] op_sel_hi:[0,1,1]
	v_pk_fma_f32 v[14:15], v[64:65], v[46:47], v[14:15] op_sel_hi:[0,1,1]
	v_pk_fma_f32 v[16:17], v[66:67], v[46:47], v[16:17] op_sel_hi:[0,1,1]
	v_pk_fma_f32 v[18:19], v[68:69], v[46:47], v[18:19] op_sel_hi:[0,1,1]
	v_pk_fma_f32 v[20:21], v[70:71], v[46:47], v[20:21] op_sel_hi:[0,1,1]
	global_store_dword v154, v54, s[14:15] offset:-4096
	s_waitcnt lgkmcnt(5)
	v_pk_mul_f32 v[38:39], v[6:7], v[80:81] op_sel_hi:[1,0]
	v_pk_mul_f32 v[40:41], v[6:7], v[80:81] op_sel:[0,1] op_sel_hi:[1,1]
	v_pk_fma_f32 v[38:39], v[8:9], v[82:83], v[38:39] op_sel_hi:[1,0,1]
	v_pk_fma_f32 v[40:41], v[8:9], v[82:83], v[40:41] op_sel:[0,1,0] op_sel_hi:[1,1,1]
	s_waitcnt lgkmcnt(3)
	v_pk_fma_f32 v[38:39], v[10:11], v[84:85], v[38:39] op_sel_hi:[1,0,1]
	v_pk_fma_f32 v[40:41], v[10:11], v[84:85], v[40:41] op_sel:[0,1,0] op_sel_hi:[1,1,1]
	v_pk_fma_f32 v[38:39], v[12:13], v[86:87], v[38:39] op_sel_hi:[1,0,1]
	v_pk_fma_f32 v[40:41], v[12:13], v[86:87], v[40:41] op_sel:[0,1,0] op_sel_hi:[1,1,1]
	v_pk_fma_f32 v[38:39], v[14:15], v[88:89], v[38:39] op_sel_hi:[1,0,1]
	v_pk_fma_f32 v[40:41], v[14:15], v[88:89], v[40:41] op_sel:[0,1,0] op_sel_hi:[1,1,1]
	v_pk_fma_f32 v[38:39], v[16:17], v[90:91], v[38:39] op_sel_hi:[1,0,1]
	v_pk_fma_f32 v[40:41], v[16:17], v[90:91], v[40:41] op_sel:[0,1,0] op_sel_hi:[1,1,1]
	s_waitcnt lgkmcnt(0)
	v_pk_fma_f32 v[38:39], v[18:19], v[92:93], v[38:39] op_sel_hi:[1,0,1]
	v_pk_fma_f32 v[40:41], v[18:19], v[92:93], v[40:41] op_sel:[0,1,0] op_sel_hi:[1,1,1]
	v_pk_fma_f32 v[38:39], v[20:21], v[94:95], v[38:39] op_sel_hi:[1,0,1]
	v_pk_fma_f32 v[40:41], v[20:21], v[94:95], v[40:41] op_sel:[0,1,0] op_sel_hi:[1,1,1]
	v_mul_f32_e32 v51, v100, v50
	v_add_f32_dpp v38, v38, v38 row_ror:8 row_mask:0xf bank_mask:0x3 bound_ctrl:1
	v_add_f32_dpp v39, v39, v39 row_ror:8 row_mask:0xf bank_mask:0x3 bound_ctrl:1
	v_add_f32_dpp v38, v40, v40 row_ror:8 row_mask:0xf bank_mask:0xc bound_ctrl:1
	v_add_f32_dpp v39, v41, v41 row_ror:8 row_mask:0xf bank_mask:0xc bound_ctrl:1
	ds_read_b128 v[56:59], v2 offset:39168
	v_add_f32_dpp v38, v38, v38 row_half_mirror row_mask:0xf bank_mask:0x5 bound_ctrl:1
	v_add_f32_dpp v38, v39, v39 row_half_mirror row_mask:0xf bank_mask:0xa bound_ctrl:1
	ds_read_b128 v[60:63], v2 offset:39424
	ds_read_b128 v[64:67], v2 offset:39680
	v_add_f32_dpp v38, v38, v38 quad_perm:[1,0,3,2] row_mask:0xf bank_mask:0xf bound_ctrl:1
	ds_read_b128 v[68:71], v2 offset:39936
	ds_read_b64 v[72:73], v3 offset:46848
	v_add_f32_dpp v38, v38, v38 quad_perm:[2,3,0,1] row_mask:0xf bank_mask:0xf bound_ctrl:1
	ds_read_b128 v[76:79], v1 offset:47456
	v_cmp_gt_f32_e32 vcc, 0x2b8cbccc, v51
	v_fmac_f32_dpp v96, -v38, v51 row_newbcast:0 row_mask:0xf bank_mask:0xf bound_ctrl:1
	v_fmac_f32_dpp v97, -v38, v51 row_newbcast:4 row_mask:0xf bank_mask:0xf bound_ctrl:1
	v_pk_mul_f32 v[44:45], v[96:97], v[100:101] op_sel:[0,1] op_sel_hi:[1,1]
	v_pk_mul_f32 v[48:49], v[44:45], v[102:103] op_sel_hi:[1,0]
	v_rcp_f32_e32 v52, v51
	s_add_u32 s14, s14, 0x1000
	s_addc_u32 s15, s15, 0
	v_fmac_f32_dpp v48, v38, v51 row_newbcast:8 row_mask:0xf bank_mask:0xf bound_ctrl:1
	v_fmac_f32_dpp v49, v38, v51 row_newbcast:12 row_mask:0xf bank_mask:0xf bound_ctrl:1
	s_cbranch_vccnz .Lgd2_rare2_5
.Lgd2_back2_5:
	v_cvt_pk_bf16_f32 v54, v48, v49
	v_pk_mul_f32 v[46:47], v[44:45], v[52:53] op_sel_hi:[1,0]
	v_pk_fma_f32 v[6:7], v[80:81], v[46:47], v[6:7] op_sel_hi:[0,1,1]
	v_pk_fma_f32 v[8:9], v[82:83], v[46:47], v[8:9] op_sel_hi:[0,1,1]
	v_pk_fma_f32 v[10:11], v[84:85], v[46:47], v[10:11] op_sel_hi:[0,1,1]
	v_pk_fma_f32 v[12:13], v[86:87], v[46:47], v[12:13] op_sel_hi:[0,1,1]
	v_pk_fma_f32 v[14:15], v[88:89], v[46:47], v[14:15] op_sel_hi:[0,1,1]
	v_pk_fma_f32 v[16:17], v[90:91], v[46:47], v[16:17] op_sel_hi:[0,1,1]
	v_pk_fma_f32 v[18:19], v[92:93], v[46:47], v[18:19] op_sel_hi:[0,1,1]
	v_pk_fma_f32 v[20:21], v[94:95], v[46:47], v[20:21] op_sel_hi:[0,1,1]
	global_store_dword v154, v54, s[14:15] offset:-4096
	s_waitcnt lgkmcnt(5)
	v_pk_mul_f32 v[38:39], v[6:7], v[56:57] op_sel_hi:[1,0]
	v_pk_mul_f32 v[40:41], v[6:7], v[56:57] op_sel:[0,1] op_sel_hi:[1,1]
	v_pk_fma_f32 v[38:39], v[8:9], v[58:59], v[38:39] op_sel_hi:[1,0,1]
	v_pk_fma_f32 v[40:41], v[8:9], v[58:59], v[40:41] op_sel:[0,1,0] op_sel_hi:[1,1,1]
	s_waitcnt lgkmcnt(3)
	v_pk_fma_f32 v[38:39], v[10:11], v[60:61], v[38:39] op_sel_hi:[1,0,1]
	v_pk_fma_f32 v[40:41], v[10:11], v[60:61], v[40:41] op_sel:[0,1,0] op_sel_hi:[1,1,1]
	v_pk_fma_f32 v[38:39], v[12:13], v[62:63], v[38:39] op_sel_hi:[1,0,1]
	v_pk_fma_f32 v[40:41], v[12:13], v[62:63], v[40:41] op_sel:[0,1,0] op_sel_hi:[1,1,1]
	v_pk_fma_f32 v[38:39], v[14:15], v[64:65], v[38:39] op_sel_hi:[1,0,1]
	v_pk_fma_f32 v[40:41], v[14:15], v[64:65], v[40:41] op_sel:[0,1,0] op_sel_hi:[1,1,1]
	v_pk_fma_f32 v[38:39], v[16:17], v[66:67], v[38:39] op_sel_hi:[1,0,1]
	v_pk_fma_f32 v[40:41], v[16:17], v[66:67], v[40:41] op_sel:[0,1,0] op_sel_hi:[1,1,1]
	s_waitcnt lgkmcnt(0)
	v_pk_fma_f32 v[38:39], v[18:19], v[68:69], v[38:39] op_sel_hi:[1,0,1]
	v_pk_fma_f32 v[40:41], v[18:19], v[68:69], v[40:41] op_sel:[0,1,0] op_sel_hi:[1,1,1]
	v_pk_fma_f32 v[38:39], v[20:21], v[70:71], v[38:39] op_sel_hi:[1,0,1]
	v_pk_fma_f32 v[40:41], v[20:21], v[70:71], v[40:41] op_sel:[0,1,0] op_sel_hi:[1,1,1]
	v_mul_f32_e32 v50, v76, v51
	v_add_f32_dpp v38, v38, v38 row_ror:8 row_mask:0xf bank_mask:0x3 bound_ctrl:1
	v_add_f32_dpp v39, v39, v39 row_ror:8 row_mask:0xf bank_mask:0x3 bound_ctrl:1
	v_add_f32_dpp v38, v40, v40 row_ror:8 row_mask:0xf bank_mask:0xc bound_ctrl:1
	v_add_f32_dpp v39, v41, v41 row_ror:8 row_mask:0xf bank_mask:0xc bound_ctrl:1
	ds_read_b128 v[80:83], v2 offset:40192
	v_add_f32_dpp v38, v38, v38 row_half_mirror row_mask:0xf bank_mask:0x5 bound_ctrl:1
	v_add_f32_dpp v38, v39, v39 row_half_mirror row_mask:0xf bank_mask:0xa bound_ctrl:1
	ds_read_b128 v[84:87], v2 offset:40448
	ds_read_b128 v[88:91], v2 offset:40704
	v_add_f32_dpp v38, v38, v38 quad_perm:[1,0,3,2] row_mask:0xf bank_mask:0xf bound_ctrl:1
	ds_read_b128 v[92:95], v2 offset:40960
	ds_read_b64 v[96:97], v3 offset:47104
	v_add_f32_dpp v38, v38, v38 quad_perm:[2,3,0,1] row_mask:0xf bank_mask:0xf bound_ctrl:1
	ds_read_b128 v[100:103], v1 offset:47472
	v_cmp_gt_f32_e32 vcc, 0x2b8cbccc, v50
	v_fmac_f32_dpp v72, -v38, v50 row_newbcast:0 row_mask:0xf bank_mask:0xf bound_ctrl:1
	v_fmac_f32_dpp v73, -v38, v50 row_newbcast:4 row_mask:0xf bank_mask:0xf bound_ctrl:1
	v_pk_mul_f32 v[44:45], v[72:73], v[76:77] op_sel:[0,1] op_sel_hi:[1,1]
	v_pk_mul_f32 v[48:49], v[44:45], v[78:79] op_sel_hi:[1,0]
	v_rcp_f32_e32 v52, v50
	s_add_u32 s14, s14, 0x1000
	s_addc_u32 s15, s15, 0
	v_fmac_f32_dpp v48, v38, v50 row_newbcast:8 row_mask:0xf bank_mask:0xf bound_ctrl:1
	v_fmac_f32_dpp v49, v38, v50 row_newbcast:12 row_mask:0xf bank_mask:0xf bound_ctrl:1
	s_cbranch_vccnz .Lgd2_rare2_6
.Lgd2_back2_6:
	v_cvt_pk_bf16_f32 v54, v48, v49
	v_pk_mul_f32 v[46:47], v[44:45], v[52:53] op_sel_hi:[1,0]
	v_pk_fma_f32 v[6:7], v[56:57], v[46:47], v[6:7] op_sel_hi:[0,1,1]
	v_pk_fma_f32 v[8:9], v[58:59], v[46:47], v[8:9] op_sel_hi:[0,1,1]
	v_pk_fma_f32 v[10:11], v[60:61], v[46:47], v[10:11] op_sel_hi:[0,1,1]
	v_pk_fma_f32 v[12:13], v[62:63], v[46:47], v[12:13] op_sel_hi:[0,1,1]
	v_pk_fma_f32 v[14:15], v[64:65], v[46:47], v[14:15] op_sel_hi:[0,1,1]
	v_pk_fma_f32 v[16:17], v[66:67], v[46:47], v[16:17] op_sel_hi:[0,1,1]
	v_pk_fma_f32 v[18:19], v[68:69], v[46:47], v[18:19] op_sel_hi:[0,1,1]
	v_pk_fma_f32 v[20:21], v[70:71], v[46:47], v[20:21] op_sel_hi:[0,1,1]
	global_store_dword v154, v54, s[14:15] offset:-4096
	s_waitcnt lgkmcnt(5)
	v_pk_mul_f32 v[38:39], v[6:7], v[80:81] op_sel_hi:[1,0]
	v_pk_mul_f32 v[40:41], v[6:7], v[80:81] op_sel:[0,1] op_sel_hi:[1,1]
	v_pk_fma_f32 v[38:39], v[8:9], v[82:83], v[38:39] op_sel_hi:[1,0,1]
	v_pk_fma_f32 v[40:41], v[8:9], v[82:83], v[40:41] op_sel:[0,1,0] op_sel_hi:[1,1,1]
	s_waitcnt lgkmcnt(3)
	v_pk_fma_f32 v[38:39], v[10:11], v[84:85], v[38:39] op_sel_hi:[1,0,1]
	v_pk_fma_f32 v[40:41], v[10:11], v[84:85], v[40:41] op_sel:[0,1,0] op_sel_hi:[1,1,1]
	v_pk_fma_f32 v[38:39], v[12:13], v[86:87], v[38:39] op_sel_hi:[1,0,1]
	v_pk_fma_f32 v[40:41], v[12:13], v[86:87], v[40:41] op_sel:[0,1,0] op_sel_hi:[1,1,1]
	v_pk_fma_f32 v[38:39], v[14:15], v[88:89], v[38:39] op_sel_hi:[1,0,1]
	v_pk_fma_f32 v[40:41], v[14:15], v[88:89], v[40:41] op_sel:[0,1,0] op_sel_hi:[1,1,1]
	v_pk_fma_f32 v[38:39], v[16:17], v[90:91], v[38:39] op_sel_hi:[1,0,1]
	v_pk_fma_f32 v[40:41], v[16:17], v[90:91], v[40:41] op_sel:[0,1,0] op_sel_hi:[1,1,1]
	s_waitcnt lgkmcnt(0)
	v_pk_fma_f32 v[38:39], v[18:19], v[92:93], v[38:39] op_sel_hi:[1,0,1]
	v_pk_fma_f32 v[40:41], v[18:19], v[92:93], v[40:41] op_sel:[0,1,0] op_sel_hi:[1,1,1]
	v_pk_fma_f32 v[38:39], v[20:21], v[94:95], v[38:39] op_sel_hi:[1,0,1]
	v_pk_fma_f32 v[40:41], v[20:21], v[94:95], v[40:41] op_sel:[0,1,0] op_sel_hi:[1,1,1]
	v_mul_f32_e32 v51, v100, v50
	v_add_f32_dpp v38, v38, v38 row_ror:8 row_mask:0xf bank_mask:0x3 bound_ctrl:1
	v_add_f32_dpp v39, v39, v39 row_ror:8 row_mask:0xf bank_mask:0x3 bound_ctrl:1
	v_add_f32_dpp v38, v40, v40 row_ror:8 row_mask:0xf bank_mask:0xc bound_ctrl:1
	v_add_f32_dpp v39, v41, v41 row_ror:8 row_mask:0xf bank_mask:0xc bound_ctrl:1
	ds_read_b128 v[56:59], v2 offset:256
	v_add_f32_dpp v38, v38, v38 row_half_mirror row_mask:0xf bank_mask:0x5 bound_ctrl:1
	v_add_f32_dpp v38, v39, v39 row_half_mirror row_mask:0xf bank_mask:0xa bound_ctrl:1
	ds_read_b128 v[60:63], v2 offset:512
	ds_read_b128 v[64:67], v2 offset:768
	v_add_f32_dpp v38, v38, v38 quad_perm:[1,0,3,2] row_mask:0xf bank_mask:0xf bound_ctrl:1
	ds_read_b128 v[68:71], v2 offset:1024
	ds_read_b64 v[72:73], v3 offset:12544
	v_add_f32_dpp v38, v38, v38 quad_perm:[2,3,0,1] row_mask:0xf bank_mask:0xf bound_ctrl:1
	ds_read_b128 v[76:79], v1 offset:14592
	v_cmp_gt_f32_e32 vcc, 0x2b8cbccc, v51
	v_fmac_f32_dpp v96, -v38, v51 row_newbcast:0 row_mask:0xf bank_mask:0xf bound_ctrl:1
	v_fmac_f32_dpp v97, -v38, v51 row_newbcast:4 row_mask:0xf bank_mask:0xf bound_ctrl:1
	v_pk_mul_f32 v[44:45], v[96:97], v[100:101] op_sel:[0,1] op_sel_hi:[1,1]
	v_pk_mul_f32 v[48:49], v[44:45], v[102:103] op_sel_hi:[1,0]
	v_rcp_f32_e32 v52, v51
	s_add_u32 s14, s14, 0x1000
	s_addc_u32 s15, s15, 0
	v_fmac_f32_dpp v48, v38, v51 row_newbcast:8 row_mask:0xf bank_mask:0xf bound_ctrl:1
	v_fmac_f32_dpp v49, v38, v51 row_newbcast:12 row_mask:0xf bank_mask:0xf bound_ctrl:1
	s_cbranch_vccnz .Lgd2_rare2_7
